# speedup vs baseline: 1.0158x; 1.0013x over previous
; #define BAR __builtin_amdgcn_s_barrier()
; template <bool PRE, bool NEXT> ...
;     ...
;   const int wid = __builtin_amdgcn_readfirstlane(tid >> 6), lane = tid & 63, wr = wid >> 2, wc = wid & 3, fr = lane & 15, fq = lane >> 4;
;   unsigned off0_A, off1_A, off0_Bt, off1_Bt;
;   { int r0, c0, r1, c1; stage_rc(tid * 16, r0, c0); stage_rc(tid * 16 + 8192, r1, c1);
;     off0_A = r0 * lda + c0; off1_A = r1 * lda + c1; off0_Bt = r0 * ldb + c0; off1_Bt = r1 * ldb + c1; }
;   bf16x8 At[4][2], B0[2][2], B1[2][2];
;   const int nt = K / BK;
;   if constexpr (!PRE) {
;     STAGE(SB(0, 0), Bt, ldb, 0, 0); STAGE(SA(0, 0), A, lda, 0, 0);
;     STAGE(SB(0, 1), Bt, ldb, HALF, 0); STAGE(SA(0, 1), A, lda, HALF, 0);
;   }
;   if (wr == 1) BAR;
; template <int MODE, bool PRE = false, bool NEXT = false> ...
;     ...
; #pragma unroll
;   for (int ai = 0; ai < 2; ++ai)
; #pragma unroll
;     for (int bj = 0; bj < 2; ++bj)
; #pragma unroll
;       for (int m = 0; m < 4; ++m)
; #pragma unroll
;         for (int n = 0; n < 2; ++n) acc[ai][bj][m][n] = f32x4{0.f, 0.f, 0.f, 0.f};
.LBB0_300:
	v_mov_b32_e32 v141, v181
	s_barrier
	s_ashr_i32 s7, s6, 31
	v_ashrrev_i32_e32 v0, 31, v141
	v_lshrrev_b32_e32 v0, 26, v0
	v_add_u32_e32 v0, v141, v0
	v_ashrrev_i32_e32 v10, 6, v0
	v_bfe_i32 v0, v141, 27, 1
	v_lshlrev_b32_e32 v18, 4, v141
	v_lshrrev_b32_e32 v0, 22, v0
	v_add_u32_e32 v0, v18, v0
	v_and_b32_e32 v0, 0xfffffc00, v0
	v_sub_u32_e32 v0, v18, v0
	v_lshrrev_b32_e32 v2, 4, v0
	v_bitop3_b32 v2, v2, v0, 32 bitop3:0x6c
	v_ashrrev_i32_e32 v0, 31, v0
	v_lshrrev_b32_e32 v0, 26, v0
	v_lshlrev_b32_e32 v3, 3, v10
	v_add_u32_e32 v0, v2, v0
	v_and_b32_e32 v3, 0x3ffff0, v3
	v_ashrrev_i32_e32 v11, 6, v0
	v_add_u32_e32 v0, v11, v3
	v_lshlrev_b32_e32 v3, 5, v10
	v_and_b32_e32 v12, 32, v3
	v_mul_i32_i24_e32 v3, 64, v11
	v_sub_u32_e32 v2, v2, v3
	v_ashrrev_i16_sdwa v14, v190, sext(v2) dst_sel:DWORD dst_unused:UNUSED_PAD src0_sel:DWORD src1_sel:BYTE_0
	v_add_u32_e32 v2, 0x2000, v18
	v_ashrrev_i32_e32 v3, 31, v2
	v_lshrrev_b32_e32 v3, 22, v3
	v_add_u32_e32 v3, v2, v3
	v_ashrrev_i32_e32 v13, 10, v3
	v_mul_i32_i24_e32 v3, 0x400, v13
	v_sub_u32_e32 v2, v2, v3
	v_lshrrev_b32_e32 v3, 4, v2
	v_bitop3_b32 v2, v3, v2, 32 bitop3:0x6c
	v_ashrrev_i32_e32 v4, 31, v2
	s_lshl_b64 s[10:11], s[6:7], 19
	v_readlane_b32 s0, v253, 58
	v_lshrrev_b32_e32 v4, 26, v4
	s_add_u32 s0, s0, s10
	v_readlane_b32 s1, v253, 59
	v_lshlrev_b32_e32 v3, 3, v13
	v_add_u32_e32 v4, v2, v4
	s_addc_u32 s1, s1, s11
	s_ashr_i32 s9, s8, 31
	v_and_b32_e32 v3, 0x3ffff0, v3
	v_ashrrev_i32_e32 v15, 6, v4
	v_lshlrev_b32_e32 v5, 5, v13
	v_and_b32_e32 v4, 0xc0, v4
	s_lshl_b64 s[64:65], s[8:9], 19
	v_add_u32_e32 v3, v15, v3
	v_and_b32_e32 v16, 32, v5
	v_sub_u32_e32 v2, v2, v4
	v_lshl_or_b32 v0, v0, 10, v12
	s_add_u32 s80, s18, s64
	v_ashrrev_i16_sdwa v17, v190, sext(v2) dst_sel:DWORD dst_unused:UNUSED_PAD src0_sel:DWORD src1_sel:BYTE_0
	v_add_u32_sdwa v0, v0, sext(v14) dst_sel:DWORD dst_unused:UNUSED_PAD src0_sel:DWORD src1_sel:WORD_0
	v_lshl_or_b32 v2, v3, 10, v16
	v_add_u32_e32 v145, s33, v18
	s_addc_u32 s81, s19, s65
	v_add_u32_sdwa v130, v2, sext(v17) dst_sel:DWORD dst_unused:UNUSED_PAD src0_sel:DWORD src1_sel:WORD_0
	v_lshlrev_b64 v[20:21], 1, v[0:1]
	v_readfirstlane_b32 s30, v145
	v_mov_b32_e32 v131, v1
	v_add_u32_e32 v146, 0x2000, v145
	v_lshl_add_u64 v[2:3], s[80:81], 0, v[20:21]
	s_mov_b32 m0, s30
	v_lshlrev_b64 v[22:23], 1, v[130:131]
	v_readfirstlane_b32 s30, v146
	v_add_u32_e32 v147, 16, v18
	v_readfirstlane_b32 s9, v141
	global_load_lds_dwordx4 v[2:3], off
	v_lshl_add_u64 v[6:7], s[80:81], 0, v[22:23]
	s_mov_b32 m0, s30
	v_readfirstlane_b32 s30, v147
	v_add_u32_e32 v148, 0x2000, v147
	s_ashr_i32 s13, s9, 8
	global_load_lds_dwordx4 v[6:7], off
	v_lshl_add_u64 v[8:9], s[0:1], 0, v[20:21]
	s_mov_b32 m0, s30
	v_readfirstlane_b32 s30, v148
	global_load_lds_dwordx4 v[8:9], off
	s_mov_b32 m0, s30
	s_add_u32 s30, s80, 0x40000
	v_add_u32_e32 v150, s38, v18
	v_lshl_add_u64 v[4:5], s[0:1], 0, v[22:23]
	s_addc_u32 s31, s81, 0
	v_readfirstlane_b32 s58, v150
	global_load_lds_dwordx4 v[4:5], off
	v_lshl_add_u64 v[24:25], s[30:31], 0, v[20:21]
	s_mov_b32 m0, s58
	v_add_u32_e32 v151, 0x2000, v150
	global_load_lds_dwordx4 v[24:25], off
	v_lshl_add_u64 v[24:25], s[30:31], 0, v[22:23]
	v_readfirstlane_b32 s30, v151
	s_mov_b32 m0, s30
	s_add_u32 s30, s0, 0x40000
	v_add_u32_e32 v152, 0x4000, v147
	s_addc_u32 s31, s1, 0
	v_readfirstlane_b32 s58, v152
	global_load_lds_dwordx4 v[24:25], off
	v_lshl_add_u64 v[20:21], s[30:31], 0, v[20:21]
	s_mov_b32 m0, s58
	v_add_u32_e32 v153, 0x6000, v147
	global_load_lds_dwordx4 v[20:21], off
	v_lshl_add_u64 v[20:21], s[30:31], 0, v[22:23]
	v_readfirstlane_b32 s30, v153
	s_mov_b32 m0, s30
	s_cmp_lg_u32 s13, 1
	global_load_lds_dwordx4 v[20:21], off
	v_mov_b32_e32 v26, 0
	v_mov_b32_e32 v27, 0
	v_mov_b32_e32 v28, 0
	v_mov_b32_e32 v29, 0
	v_mov_b32_e32 v30, 0
	v_mov_b32_e32 v31, 0
	v_mov_b32_e32 v32, 0
	v_mov_b32_e32 v33, 0
	v_mov_b32_e32 v34, 0
	v_mov_b32_e32 v35, 0
	v_mov_b32_e32 v36, 0
	v_mov_b32_e32 v37, 0
	v_mov_b32_e32 v38, 0
	v_mov_b32_e32 v39, 0
	v_mov_b32_e32 v40, 0
	v_mov_b32_e32 v41, 0
	v_mov_b32_e32 v42, 0
	v_mov_b32_e32 v43, 0
	v_mov_b32_e32 v44, 0
	v_mov_b32_e32 v45, 0
	v_mov_b32_e32 v46, 0
	v_mov_b32_e32 v47, 0
	v_mov_b32_e32 v48, 0
	v_mov_b32_e32 v49, 0
	v_mov_b32_e32 v50, 0
	v_mov_b32_e32 v51, 0
	v_mov_b32_e32 v52, 0
	v_mov_b32_e32 v53, 0
	v_mov_b32_e32 v54, 0
	v_mov_b32_e32 v55, 0
	v_mov_b32_e32 v56, 0
	v_mov_b32_e32 v57, 0
	v_mov_b32_e32 v58, 0
	v_mov_b32_e32 v59, 0
	v_mov_b32_e32 v60, 0
	v_mov_b32_e32 v61, 0
	v_mov_b32_e32 v62, 0
	v_mov_b32_e32 v63, 0
	v_mov_b32_e32 v64, 0
	v_mov_b32_e32 v65, 0
	v_mov_b32_e32 v66, 0
	v_mov_b32_e32 v67, 0
	v_mov_b32_e32 v68, 0
	v_mov_b32_e32 v69, 0
	v_mov_b32_e32 v70, 0
	v_mov_b32_e32 v71, 0
	v_mov_b32_e32 v72, 0
	v_mov_b32_e32 v73, 0
	v_mov_b32_e32 v74, 0
	v_mov_b32_e32 v75, 0
	v_mov_b32_e32 v76, 0
	v_mov_b32_e32 v77, 0
	v_mov_b32_e32 v78, 0
	v_mov_b32_e32 v79, 0
	v_mov_b32_e32 v80, 0
	v_mov_b32_e32 v81, 0
	v_mov_b32_e32 v82, 0
	v_mov_b32_e32 v83, 0
	v_mov_b32_e32 v84, 0
	v_mov_b32_e32 v85, 0
	v_mov_b32_e32 v86, 0
	v_mov_b32_e32 v87, 0
	v_mov_b32_e32 v88, 0
	v_mov_b32_e32 v89, 0
	v_mov_b32_e32 v90, 0
	v_mov_b32_e32 v91, 0
	v_mov_b32_e32 v92, 0
	v_mov_b32_e32 v93, 0
	v_mov_b32_e32 v94, 0
	v_mov_b32_e32 v95, 0
	v_mov_b32_e32 v96, 0
	v_mov_b32_e32 v97, 0
	v_mov_b32_e32 v98, 0
	v_mov_b32_e32 v99, 0
	v_mov_b32_e32 v100, 0
	v_mov_b32_e32 v101, 0
	v_mov_b32_e32 v102, 0
	v_mov_b32_e32 v103, 0
	v_mov_b32_e32 v104, 0
	v_mov_b32_e32 v105, 0
	v_mov_b32_e32 v106, 0
	v_mov_b32_e32 v107, 0
	v_mov_b32_e32 v108, 0
	v_mov_b32_e32 v109, 0
	v_mov_b32_e32 v110, 0
	v_mov_b32_e32 v111, 0
	v_mov_b32_e32 v112, 0
	v_mov_b32_e32 v113, 0
	v_mov_b32_e32 v114, 0
	v_mov_b32_e32 v115, 0
	v_mov_b32_e32 v116, 0
	v_mov_b32_e32 v117, 0
	v_mov_b32_e32 v118, 0
	v_mov_b32_e32 v119, 0
	v_mov_b32_e32 v120, 0
	v_mov_b32_e32 v121, 0
	v_mov_b32_e32 v122, 0
	v_mov_b32_e32 v123, 0
	v_mov_b32_e32 v124, 0
	v_mov_b32_e32 v125, 0
	v_mov_b32_e32 v126, 0
	v_mov_b32_e32 v127, 0
	v_mov_b32_e32 v128, 0
	v_mov_b32_e32 v129, 0
	s_cbranch_scc1 .LBB0_302
	s_barrier
; #define WAIT_V(n) asm volatile("s_waitcnt vmcnt(" #n ")" ::: "memory")
; #define BAR __builtin_amdgcn_s_barrier()
; template <bool PRE, bool NEXT> ...
;     ...
;   const int wid = __builtin_amdgcn_readfirstlane(tid >> 6), lane = tid & 63, wr = wid >> 2, wc = wid & 3, fr = lane & 15, fq = lane >> 4;
;   unsigned off0_A, off1_A, off0_Bt, off1_Bt;
;   { int r0, c0, r1, c1; stage_rc(tid * 16, r0, c0); stage_rc(tid * 16 + 8192, r1, c1);
;     off0_A = r0 * lda + c0; off1_A = r1 * lda + c1; off0_Bt = r0 * ldb + c0; off1_Bt = r1 * ldb + c1; }
;   bf16x8 At[4][2], B0[2][2], B1[2][2];
;   const int nt = K / BK;
;   if constexpr (!PRE) {
;     STAGE(SB(0, 0), Bt, ldb, 0, 0); STAGE(SA(0, 0), A, lda, 0, 0);
;     STAGE(SB(0, 1), Bt, ldb, HALF, 0); STAGE(SA(0, 1), A, lda, HALF, 0);
;   }
;   if (wr == 1) BAR;
;   if constexpr (PRE) WAIT_V(0); else WAIT_V(4);
;   BAR;
;   STAGE(SB(1, 0), Bt, ldb, 0, 1); STAGE(SA(1, 0), A, lda, 0, 1); STAGE(SB(1, 1), Bt, ldb, HALF, 1);
;   WAIT_V(6); BAR;
; template <int MODE, bool PRE = false, bool NEXT = false> ...
;     ...
; #pragma unroll
;   for (int ai = 0; ai < 2; ++ai)
; #pragma unroll
;     for (int bj = 0; bj < 2; ++bj)
; #pragma unroll
;       for (int m = 0; m < 4; ++m)
; #pragma unroll
;         for (int n = 0; n < 2; ++n) acc[ai][bj][m][n] = f32x4{0.f, 0.f, 0.f, 0.f};
.LBB0_302:
	v_readlane_b32 s14, v252, 10
	s_mov_b64 s[58:59], 0x80
	v_lshl_add_u64 v[2:3], v[2:3], 0, s[58:59]
	v_add_u32_e32 v154, s14, v18
	v_add_u32_e32 v155, 0x2000, v154
	v_readfirstlane_b32 s30, v154
	s_mov_b32 m0, s30
	v_readfirstlane_b32 s30, v155
	v_add_u32_e32 v156, 0x8000, v147
	s_waitcnt vmcnt(4)
	s_barrier
	global_load_lds_dwordx4 v[2:3], off
	v_lshl_add_u64 v[2:3], v[6:7], 0, s[58:59]
	s_mov_b32 m0, s30
	v_readfirstlane_b32 s30, v156
	v_add_u32_e32 v157, 0xa000, v147
	global_load_lds_dwordx4 v[2:3], off
	v_lshl_add_u64 v[2:3], v[8:9], 0, s[58:59]
	s_mov_b32 m0, s30
	v_readfirstlane_b32 s30, v157
	v_readlane_b32 s15, v252, 11
	global_load_lds_dwordx4 v[2:3], off
	s_mov_b32 m0, s30
	s_add_u32 s30, s80, 0x40080
	v_add_u32_e32 v158, s15, v18
	v_lshl_add_u64 v[2:3], v[4:5], 0, s[58:59]
	s_addc_u32 s31, s81, 0
	v_readfirstlane_b32 s58, v158
	global_load_lds_dwordx4 v[2:3], off
	v_lshl_add_u64 v[2:3], v[0:1], 1, s[30:31]
	s_mov_b32 m0, s58
	v_add_u32_e32 v159, 0x2000, v158
	global_load_lds_dwordx4 v[2:3], off
	v_lshl_add_u64 v[2:3], v[130:131], 1, s[30:31]
	v_readfirstlane_b32 s30, v159
	s_mov_b32 m0, s30
	v_and_b32_e32 v142, 15, v141
	global_load_lds_dwordx4 v[2:3], off
	v_lshlrev_b32_e32 v3, 2, v141
	v_and_b32_e32 v19, 48, v141
	v_lshlrev_b32_e32 v2, 6, v142
	v_and_b32_e32 v3, 32, v3
	v_bitop3_b32 v2, v2, v3, v19 bitop3:0x36
	v_add_u32_e32 v6, s33, v2
	v_add_u32_e32 v7, s38, v2
	v_add_u32_e32 v8, s14, v2
	v_add_u32_e32 v9, s15, v2
	s_lshl_b32 s61, s13, 13
	v_add_u32_e32 v18, 16, v2
	v_lshlrev_b32_e32 v2, 6, v141
	s_movk_i32 s13, 0x3c0
	v_and_or_b32 v2, v2, s13, v19
	v_xad_u32 v161, v2, v3, 16
	v_lshlrev_b32_e32 v2, 13, v10
	v_and_b32_e32 v2, 0xffffc000, v2
	v_lshlrev_b32_e32 v4, 13, v13
	s_lshl_b32 s30, s9, 6
	v_lshl_add_u32 v2, v11, 10, v2
	v_and_b32_e32 v4, 0xffffc000, v4
	s_and_b32 s60, s30, 0x3000
	s_or_b32 s13, s61, 0x800
	s_or_b32 s30, s61, 0x1000
	s_or_b32 s31, s61, 0x1800
	v_or_b32_e32 v2, v2, v12
	v_lshl_add_u32 v4, v15, 10, v4
	s_add_u32 s58, s17, s64
	v_add_u32_sdwa v2, v2, sext(v14) dst_sel:DWORD dst_unused:UNUSED_PAD src0_sel:DWORD src1_sel:WORD_0
	v_mov_b32_e32 v3, v1
	v_or_b32_e32 v4, v4, v16
	s_waitcnt vmcnt(6)
	s_addc_u32 s59, 0, s65
	v_lshlrev_b64 v[2:3], 1, v[2:3]
	v_add_u32_sdwa v4, v4, sext(v17) dst_sel:DWORD dst_unused:UNUSED_PAD src0_sel:DWORD src1_sel:WORD_0
	v_mov_b32_e32 v5, v1
	v_lshl_add_u64 v[132:133], s[58:59], 0, v[2:3]
	v_lshlrev_b64 v[4:5], 1, v[4:5]
	v_lshl_add_u64 v[136:137], s[10:11], 0, v[2:3]
	v_mov_b32_e32 v2, 0
	v_lshl_add_u64 v[134:135], s[58:59], 0, v[4:5]
	v_lshl_add_u64 v[138:139], s[10:11], 0, v[4:5]
	s_mov_b32 s10, -2
	v_add_u32_e32 v162, s60, v6
	v_add_u32_e32 v143, s61, v18
	v_add_u32_e32 v160, s60, v7
	v_add_u32_e32 v149, s60, v8
	v_add_u32_e32 v144, s60, v9
	v_mov_b32_e32 v3, v2
	v_mov_b32_e32 v4, v2
	v_mov_b32_e32 v5, v2
	v_mov_b32_e32 v6, v2
	v_mov_b32_e32 v7, v2
	v_mov_b32_e32 v8, v2
	v_mov_b32_e32 v9, v2
	v_mov_b32_e32 v10, v2
	v_mov_b32_e32 v11, v2
	v_mov_b32_e32 v12, v2
	v_mov_b32_e32 v13, v2
	v_mov_b32_e32 v14, v2
	v_mov_b32_e32 v15, v2
	v_mov_b32_e32 v16, v2
	v_mov_b32_e32 v17, v2
	v_mov_b32_e32 v18, v2
	v_mov_b32_e32 v19, v2
	v_mov_b32_e32 v20, v2
	v_mov_b32_e32 v21, v2
	v_mov_b32_e32 v22, v2
	v_mov_b32_e32 v23, v2
	v_mov_b32_e32 v24, v2
	v_mov_b32_e32 v25, v2
	s_mov_b64 s[14:15], 0x40100
	s_mov_b64 s[58:59], 0x40180
	s_barrier

; #define BAR __builtin_amdgcn_s_barrier()
; template <bool PRE, bool NEXT> ...
;     ...
;   const int wid = __builtin_amdgcn_readfirstlane(tid >> 6), lane = tid & 63, wr = wid >> 2, wc = wid & 3, fr = lane & 15, fq = lane >> 4;
;   unsigned off0_A, off1_A, off0_Bt, off1_Bt;
;   { int r0, c0, r1, c1; stage_rc(tid * 16, r0, c0); stage_rc(tid * 16 + 8192, r1, c1);
;     off0_A = r0 * lda + c0; off1_A = r1 * lda + c1; off0_Bt = r0 * ldb + c0; off1_Bt = r1 * ldb + c1; }
;   bf16x8 At[4][2], B0[2][2], B1[2][2];
;   const int nt = K / BK;
;   if constexpr (!PRE) {
;     STAGE(SB(0, 0), Bt, ldb, 0, 0); STAGE(SA(0, 0), A, lda, 0, 0);
;     STAGE(SB(0, 1), Bt, ldb, HALF, 0); STAGE(SA(0, 1), A, lda, HALF, 0);
;   }
;   if (wr == 1) BAR;
; template <int MODE, bool PRE = false, bool NEXT = false> ...
;     ...
; #pragma unroll
;   for (int ai = 0; ai < 2; ++ai)
; #pragma unroll
;     for (int bj = 0; bj < 2; ++bj)
; #pragma unroll
;       for (int m = 0; m < 4; ++m)
; #pragma unroll
;         for (int n = 0; n < 2; ++n) acc[ai][bj][m][n] = f32x4{0.f, 0.f, 0.f, 0.f};
.LBB0_417:
	s_waitcnt vmcnt(62)
	v_mov_b32_e32 v144, v181
	s_barrier
	s_movk_i32 s14, 0x900
	v_bfe_i32 v2, v144, 27, 1
	v_lshlrev_b32_e32 v20, 4, v144
	v_lshrrev_b32_e32 v2, 22, v2
	v_add_u32_e32 v2, v20, v2
	v_and_b32_e32 v2, 0xfffffc00, v2
	v_ashrrev_i32_e32 v0, 31, v144
	v_sub_u32_e32 v2, v20, v2
	v_lshrrev_b32_e32 v0, 26, v0
	v_lshrrev_b32_e32 v3, 4, v2
	v_add_u32_e32 v0, v144, v0
	v_bitop3_b32 v3, v3, v2, 32 bitop3:0x6c
	v_ashrrev_i32_e32 v2, 31, v2
	v_ashrrev_i32_e32 v0, 6, v0
	v_lshrrev_b32_e32 v2, 26, v2
	v_lshlrev_b32_e32 v4, 3, v0
	v_add_u32_e32 v2, v3, v2
	v_and_b32_e32 v4, -16, v4
	v_ashrrev_i32_e32 v2, 6, v2
	v_lshlrev_b32_e32 v0, 5, v0
	v_add_u32_e32 v4, v2, v4
	v_and_b32_e32 v15, 32, v0
	v_mul_i32_i24_e32 v0, 64, v2
	v_add_u32_e32 v2, 0x2000, v20
	v_sub_u32_e32 v0, v3, v0
	v_ashrrev_i32_e32 v3, 31, v2
	v_lshrrev_b32_e32 v3, 22, v3
	v_add_u32_e32 v3, v2, v3
	v_ashrrev_i32_e32 v14, 10, v3
	v_mul_i32_i24_e32 v3, 0x400, v14
	v_sub_u32_e32 v2, v2, v3
	v_lshrrev_b32_e32 v3, 4, v2
	v_bitop3_b32 v2, v3, v2, 32 bitop3:0x6c
	v_ashrrev_i32_e32 v5, 31, v2
	v_lshrrev_b32_e32 v5, 26, v5
	v_add_u32_e32 v5, v2, v5
	v_ashrrev_i32_e32 v18, 6, v5
	v_and_b32_e32 v5, 0xc0, v5
	v_sub_u32_e32 v2, v2, v5
	v_ashrrev_i16_sdwa v0, v190, sext(v0) dst_sel:DWORD dst_unused:UNUSED_PAD src0_sel:DWORD src1_sel:BYTE_0
	v_lshlrev_b32_e32 v3, 3, v14
	v_lshlrev_b32_e32 v6, 5, v14
	v_ashrrev_i16_sdwa v2, v190, sext(v2) dst_sel:DWORD dst_unused:UNUSED_PAD src0_sel:DWORD src1_sel:BYTE_0
	v_bfe_i32 v16, v0, 0, 16
	v_and_b32_e32 v3, -16, v3
	v_and_b32_e32 v17, 32, v6
	v_bfe_i32 v19, v2, 0, 16
	v_add_u32_e32 v0, v15, v16
	v_add_u32_e32 v3, v18, v3
	v_add_u32_e32 v2, v17, v19
	v_mul_lo_u32 v22, v4, s58
	v_mad_u64_u32 v[6:7], s[10:11], v4, s14, v[0:1]
	v_mad_u64_u32 v[130:131], s[10:11], v3, s14, v[2:3]
	v_add_u32_e32 v0, v0, v22
	v_mul_lo_u32 v21, v3, s58
	v_add_u32_e32 v148, s33, v20
	v_add_u32_e32 v4, v2, v21
	v_lshlrev_b64 v[10:11], 1, v[0:1]
	v_readfirstlane_b32 s10, v148
	v_mov_b32_e32 v5, v1
	v_add_u32_e32 v149, 0x2000, v148
	v_lshl_add_u64 v[2:3], s[64:65], 0, v[10:11]
	s_mov_b32 m0, s10
	v_lshlrev_b64 v[24:25], 1, v[4:5]
	v_readfirstlane_b32 s10, v149
	v_mov_b32_e32 v0, v6
	v_add_u32_e32 v150, 16, v20
	v_readfirstlane_b32 s1, v144
	global_load_lds_dwordx4 v[2:3], off
	v_lshl_add_u64 v[4:5], s[64:65], 0, v[24:25]
	s_mov_b32 m0, s10
	v_lshlrev_b64 v[26:27], 1, v[0:1]
	v_readfirstlane_b32 s10, v150
	v_add_u32_e32 v151, 0x2000, v150
	s_ashr_i32 s81, s1, 8
	global_load_lds_dwordx4 v[4:5], off
	v_lshl_add_u64 v[6:7], s[12:13], 0, v[26:27]
	s_mov_b32 m0, s10
	v_mov_b32_e32 v131, v1
	v_readfirstlane_b32 s10, v151
	s_lshl_b32 s30, s58, 8
	global_load_lds_dwordx4 v[6:7], off
	v_lshlrev_b64 v[28:29], 1, v[130:131]
	s_mov_b32 m0, s10
	s_add_u32 s10, s64, s30
	v_add_u32_e32 v153, s38, v20
	v_lshl_add_u64 v[8:9], s[12:13], 0, v[28:29]
	s_addc_u32 s11, s65, 0
	v_readfirstlane_b32 s59, v153
	v_add_u32_e32 v154, 0x2000, v153
	global_load_lds_dwordx4 v[8:9], off
	v_lshl_add_u64 v[12:13], s[10:11], 0, v[10:11]
	s_mov_b32 m0, s59
	v_lshl_add_u64 v[10:11], s[10:11], 0, v[24:25]
	v_readfirstlane_b32 s10, v154
	global_load_lds_dwordx4 v[12:13], off
	s_mov_b32 m0, s10
	s_add_u32 s10, s12, 0x90000
	v_add_u32_e32 v155, 0x4000, v150
	s_addc_u32 s11, s13, 0
	v_readfirstlane_b32 s59, v155
	v_add_u32_e32 v156, 0x6000, v150
	global_load_lds_dwordx4 v[10:11], off
	v_lshl_add_u64 v[24:25], s[10:11], 0, v[26:27]
	s_mov_b32 m0, s59
	v_readfirstlane_b32 s59, v156
	global_load_lds_dwordx4 v[24:25], off
	v_lshl_add_u64 v[24:25], s[10:11], 0, v[28:29]
	s_mov_b32 m0, s59
	s_movk_i32 s15, 0x900
	global_load_lds_dwordx4 v[24:25], off
	v_mov_b32_e32 v26, 0
	v_mov_b32_e32 v27, 0
	v_mov_b32_e32 v28, 0
	v_mov_b32_e32 v29, 0
	v_mov_b32_e32 v30, 0
	v_mov_b32_e32 v31, 0
	v_mov_b32_e32 v32, 0
	v_mov_b32_e32 v33, 0
	v_mov_b32_e32 v34, 0
	v_mov_b32_e32 v35, 0
	v_mov_b32_e32 v36, 0
	v_mov_b32_e32 v37, 0
	v_mov_b32_e32 v38, 0
	v_mov_b32_e32 v39, 0
	v_mov_b32_e32 v40, 0
	v_mov_b32_e32 v41, 0
	v_mov_b32_e32 v42, 0
	v_mov_b32_e32 v43, 0
	v_mov_b32_e32 v44, 0
	v_mov_b32_e32 v45, 0
	v_mov_b32_e32 v46, 0
	v_mov_b32_e32 v47, 0
	v_mov_b32_e32 v48, 0
	v_mov_b32_e32 v49, 0
	v_mov_b32_e32 v50, 0
	v_mov_b32_e32 v51, 0
	v_mov_b32_e32 v52, 0
	v_mov_b32_e32 v53, 0
	v_mov_b32_e32 v54, 0
	v_mov_b32_e32 v55, 0
	v_mov_b32_e32 v56, 0
	v_mov_b32_e32 v57, 0
	v_mov_b32_e32 v58, 0
	v_mov_b32_e32 v59, 0
	v_mov_b32_e32 v60, 0
	v_mov_b32_e32 v61, 0
	v_mov_b32_e32 v62, 0
	v_mov_b32_e32 v63, 0
	v_mov_b32_e32 v64, 0
	v_mov_b32_e32 v65, 0
	v_mov_b32_e32 v66, 0
	v_mov_b32_e32 v67, 0
	v_mov_b32_e32 v68, 0
	v_mov_b32_e32 v69, 0
	v_mov_b32_e32 v70, 0
	v_mov_b32_e32 v71, 0
	v_mov_b32_e32 v72, 0
	v_mov_b32_e32 v73, 0
	v_mov_b32_e32 v74, 0
	v_mov_b32_e32 v75, 0
	v_mov_b32_e32 v76, 0
	v_mov_b32_e32 v77, 0
	v_mov_b32_e32 v78, 0
	v_mov_b32_e32 v79, 0
	v_mov_b32_e32 v80, 0
	v_mov_b32_e32 v81, 0
	v_mov_b32_e32 v82, 0
	v_mov_b32_e32 v83, 0
	v_mov_b32_e32 v84, 0
	v_mov_b32_e32 v85, 0
	v_mov_b32_e32 v86, 0
	v_mov_b32_e32 v87, 0
	v_mov_b32_e32 v88, 0
	v_mov_b32_e32 v89, 0
	v_mov_b32_e32 v90, 0
	v_mov_b32_e32 v91, 0
	v_mov_b32_e32 v92, 0
	v_mov_b32_e32 v93, 0
	v_mov_b32_e32 v94, 0
	v_mov_b32_e32 v95, 0
	v_mov_b32_e32 v96, 0
	v_mov_b32_e32 v97, 0
	v_mov_b32_e32 v98, 0
	v_mov_b32_e32 v99, 0
	v_mov_b32_e32 v100, 0
	v_mov_b32_e32 v101, 0
	v_mov_b32_e32 v102, 0
	v_mov_b32_e32 v103, 0
	v_mov_b32_e32 v104, 0
	v_mov_b32_e32 v105, 0
	v_mov_b32_e32 v106, 0
	v_mov_b32_e32 v107, 0
	v_mov_b32_e32 v108, 0
	v_mov_b32_e32 v109, 0
	v_mov_b32_e32 v110, 0
	v_mov_b32_e32 v111, 0
	v_mov_b32_e32 v112, 0
	v_mov_b32_e32 v113, 0
	v_mov_b32_e32 v114, 0
	v_mov_b32_e32 v115, 0
	v_mov_b32_e32 v116, 0
	v_mov_b32_e32 v117, 0
	v_mov_b32_e32 v118, 0
	v_mov_b32_e32 v119, 0
	v_mov_b32_e32 v120, 0
	v_mov_b32_e32 v121, 0
	v_mov_b32_e32 v122, 0
	v_mov_b32_e32 v123, 0
	v_mov_b32_e32 v124, 0
	v_mov_b32_e32 v125, 0
	v_mov_b32_e32 v126, 0
	v_mov_b32_e32 v127, 0
	v_mov_b32_e32 v128, 0
	v_mov_b32_e32 v129, 0
	s_cmp_lg_u32 s81, 1
	s_cbranch_scc1 .LBB0_419
	s_barrier
; #define WAIT_V(n) asm volatile("s_waitcnt vmcnt(" #n ")" ::: "memory")
; #define BAR __builtin_amdgcn_s_barrier()
; template <bool PRE, bool NEXT> ...
;     ...
;   const int wid = __builtin_amdgcn_readfirstlane(tid >> 6), lane = tid & 63, wr = wid >> 2, wc = wid & 3, fr = lane & 15, fq = lane >> 4;
;   unsigned off0_A, off1_A, off0_Bt, off1_Bt;
;   { int r0, c0, r1, c1; stage_rc(tid * 16, r0, c0); stage_rc(tid * 16 + 8192, r1, c1);
;     off0_A = r0 * lda + c0; off1_A = r1 * lda + c1; off0_Bt = r0 * ldb + c0; off1_Bt = r1 * ldb + c1; }
;   bf16x8 At[4][2], B0[2][2], B1[2][2];
;   const int nt = K / BK;
;   if constexpr (!PRE) {
;     STAGE(SB(0, 0), Bt, ldb, 0, 0); STAGE(SA(0, 0), A, lda, 0, 0);
;     STAGE(SB(0, 1), Bt, ldb, HALF, 0); STAGE(SA(0, 1), A, lda, HALF, 0);
;   }
;   if (wr == 1) BAR;
;   if constexpr (PRE) WAIT_V(0); else WAIT_V(4);
;   BAR;
;   STAGE(SB(1, 0), Bt, ldb, 0, 1); STAGE(SA(1, 0), A, lda, 0, 1); STAGE(SB(1, 1), Bt, ldb, HALF, 1);
;   WAIT_V(6); BAR;
; template <int MODE, bool PRE = false, bool NEXT = false> ...
;     ...
; #pragma unroll
;   for (int ai = 0; ai < 2; ++ai)
; #pragma unroll
;     for (int bj = 0; bj < 2; ++bj)
; #pragma unroll
;       for (int m = 0; m < 4; ++m)
; #pragma unroll
;         for (int n = 0; n < 2; ++n) acc[ai][bj][m][n] = f32x4{0.f, 0.f, 0.f, 0.f};
.LBB0_419:
	v_readlane_b32 s14, v252, 10
	s_mov_b64 vcc, 0x80
	v_lshl_add_u64 v[2:3], v[2:3], 0, vcc
	v_add_u32_e32 v157, s14, v20
	v_add_u32_e32 v158, 0x2000, v157
	v_readfirstlane_b32 s60, v157
	s_mov_b32 m0, s60
	v_readfirstlane_b32 s60, v158
	v_add_u32_e32 v159, 0x8000, v150
	s_waitcnt vmcnt(4)
	s_barrier
	global_load_lds_dwordx4 v[2:3], off
	v_lshl_add_u64 v[2:3], v[4:5], 0, vcc
	s_mov_b32 m0, s60
	v_readfirstlane_b32 s60, v159
	v_add_u32_e32 v160, 0xa000, v150
	v_readlane_b32 s22, v252, 11
	global_load_lds_dwordx4 v[2:3], off
	v_lshl_add_u64 v[2:3], v[6:7], 0, vcc
	s_mov_b32 m0, s60
	v_readfirstlane_b32 s60, v160
	v_add_u32_e32 v161, s22, v20
	global_load_lds_dwordx4 v[2:3], off
	v_lshl_add_u64 v[2:3], v[8:9], 0, vcc
	s_mov_b32 m0, s60
	v_readfirstlane_b32 s60, v161
	v_add_u32_e32 v162, 0x2000, v161
	global_load_lds_dwordx4 v[2:3], off
	v_lshl_add_u64 v[2:3], v[12:13], 0, vcc
	s_mov_b32 m0, s60
	v_readfirstlane_b32 s60, v162
	global_load_lds_dwordx4 v[2:3], off
	v_lshl_add_u64 v[2:3], v[10:11], 0, vcc
	s_mov_b32 m0, s60
	v_and_b32_e32 v145, 15, v144
	global_load_lds_dwordx4 v[2:3], off
	v_lshlrev_b32_e32 v3, 2, v144
	v_and_b32_e32 v23, 48, v144
	v_lshlrev_b32_e32 v2, 6, v145
	v_and_b32_e32 v3, 32, v3
	s_lshl_b32 s60, s1, 6
	v_lshrrev_b32_e32 v7, 1, v14
	v_mul_lo_u32 v6, v18, s15
	s_mov_b32 s15, 0x9000
	v_bitop3_b32 v2, v2, v3, v23 bitop3:0x36
	s_and_b32 s31, s60, 0x3000
	v_mad_u64_u32 v[6:7], s[60:61], v7, s15, v[6:7]
	s_lshr_b32 s59, s58, 6
	v_add_u32_e32 v8, s33, v2
	v_add_u32_e32 v9, s38, v2
	v_add_u32_e32 v10, s14, v2
	v_add_u32_e32 v11, s22, v2
	s_lshl_b32 vcc_hi, s81, 13
	v_add_u32_e32 v12, 16, v2
	v_lshlrev_b32_e32 v2, 6, v144
	s_movk_i32 s14, 0x3c0
	v_or_b32_e32 v6, v6, v17
	s_add_i32 s59, s59, -2
	v_and_or_b32 v2, v2, s14, v23
	s_or_b32 vcc_lo, vcc_hi, 0x800
	s_or_b32 s14, vcc_hi, 0x1000
	s_or_b32 s81, vcc_hi, 0x1800
	v_add_u32_e32 v6, v6, v19
	v_mov_b32_e32 v7, v1
	v_xad_u32 v165, v2, v3, 16
	v_add3_u32 v2, v22, v15, v16
	v_mov_b32_e32 v3, v1
	v_lshl_add_u64 v[136:137], v[0:1], 1, s[12:13]
	v_lshl_add_u64 v[138:139], v[6:7], 1, s[12:13]
	s_add_u32 s12, s64, s30
	s_waitcnt vmcnt(6)
	v_lshlrev_b64 v[2:3], 1, v[2:3]
	v_add3_u32 v4, v21, v17, v19
	v_mov_b32_e32 v5, v1
	s_addc_u32 s13, s65, 0
	v_lshl_add_u64 v[132:133], s[64:65], 0, v[2:3]
	v_lshlrev_b64 v[4:5], 1, v[4:5]
	v_lshl_add_u64 v[140:141], s[12:13], 0, v[2:3]
	v_mov_b32_e32 v2, 0
	v_lshl_add_u64 v[134:135], s[64:65], 0, v[4:5]
	v_lshl_add_u64 v[142:143], s[12:13], 0, v[4:5]
	s_mov_b32 s64, 0
	s_mov_b64 s[12:13], 0
	v_add_u32_e32 v166, s31, v8
	v_add_u32_e32 v146, vcc_hi, v12
	v_add_u32_e32 v163, s31, v9
	v_add_u32_e32 v152, s31, v10
	v_add_u32_e32 v147, s31, v11
	v_mov_b32_e32 v3, v2
	v_mov_b32_e32 v4, v2
	v_mov_b32_e32 v5, v2
	v_mov_b32_e32 v6, v2
	v_mov_b32_e32 v7, v2
	v_mov_b32_e32 v8, v2
	v_mov_b32_e32 v9, v2
	v_mov_b32_e32 v10, v2
	v_mov_b32_e32 v11, v2
	v_mov_b32_e32 v12, v2
	v_mov_b32_e32 v13, v2
	v_mov_b32_e32 v14, v2
	v_mov_b32_e32 v15, v2
	v_mov_b32_e32 v16, v2
	v_mov_b32_e32 v17, v2
	v_mov_b32_e32 v18, v2
	v_mov_b32_e32 v19, v2
	v_mov_b32_e32 v20, v2
	v_mov_b32_e32 v21, v2
	v_mov_b32_e32 v22, v2
	v_mov_b32_e32 v23, v2
	v_mov_b32_e32 v24, v2
	v_mov_b32_e32 v25, v2
	s_mov_b64 s[30:31], 0x90080
	s_mov_b64 s[60:61], 0x90100
	s_barrier

; #define BAR __builtin_amdgcn_s_barrier()
; template <bool PRE, bool NEXT> ...
;     ...
;   const int wid = __builtin_amdgcn_readfirstlane(tid >> 6), lane = tid & 63, wr = wid >> 2, wc = wid & 3, fr = lane & 15, fq = lane >> 4;
;   unsigned off0_A, off1_A, off0_Bt, off1_Bt;
;   { int r0, c0, r1, c1; stage_rc(tid * 16, r0, c0); stage_rc(tid * 16 + 8192, r1, c1);
;     off0_A = r0 * lda + c0; off1_A = r1 * lda + c1; off0_Bt = r0 * ldb + c0; off1_Bt = r1 * ldb + c1; }
;   bf16x8 At[4][2], B0[2][2], B1[2][2];
;   const int nt = K / BK;
;   if constexpr (!PRE) {
;     STAGE(SB(0, 0), Bt, ldb, 0, 0); STAGE(SA(0, 0), A, lda, 0, 0);
;     STAGE(SB(0, 1), Bt, ldb, HALF, 0); STAGE(SA(0, 1), A, lda, HALF, 0);
;   }
;   if (wr == 1) BAR;
; template <int MODE, bool PRE = false, bool NEXT = false> ...
;     ...
; #pragma unroll
;   for (int ai = 0; ai < 2; ++ai)
; #pragma unroll
;     for (int bj = 0; bj < 2; ++bj)
; #pragma unroll
;       for (int m = 0; m < 4; ++m)
; #pragma unroll
;         for (int n = 0; n < 2; ++n) acc[ai][bj][m][n] = f32x4{0.f, 0.f, 0.f, 0.f};
.LBB0_536:
	v_mov_b32_e32 v140, v181
	s_waitcnt vmcnt(63) expcnt(7) lgkmcnt(15)
	s_barrier
	s_ashr_i32 s9, s8, 31
	v_ashrrev_i32_e32 v0, 31, v140
	v_lshrrev_b32_e32 v0, 26, v0
	v_add_u32_e32 v0, v140, v0
	v_ashrrev_i32_e32 v10, 6, v0
	v_bfe_i32 v0, v140, 27, 1
	v_lshlrev_b32_e32 v18, 4, v140
	v_lshrrev_b32_e32 v0, 22, v0
	v_add_u32_e32 v0, v18, v0
	v_and_b32_e32 v0, 0xfffffc00, v0
	v_sub_u32_e32 v0, v18, v0
	v_lshrrev_b32_e32 v2, 4, v0
	v_bitop3_b32 v2, v2, v0, 32 bitop3:0x6c
	v_ashrrev_i32_e32 v0, 31, v0
	v_lshrrev_b32_e32 v0, 26, v0
	v_lshlrev_b32_e32 v3, 3, v10
	v_add_u32_e32 v0, v2, v0
	v_and_b32_e32 v3, 0x3ffff0, v3
	v_ashrrev_i32_e32 v11, 6, v0
	v_add_u32_e32 v0, v11, v3
	v_lshlrev_b32_e32 v3, 5, v10
	v_and_b32_e32 v12, 32, v3
	v_mul_i32_i24_e32 v3, 64, v11
	v_sub_u32_e32 v2, v2, v3
	v_ashrrev_i16_sdwa v14, v190, sext(v2) dst_sel:DWORD dst_unused:UNUSED_PAD src0_sel:DWORD src1_sel:BYTE_0
	v_add_u32_e32 v2, 0x2000, v18
	v_ashrrev_i32_e32 v3, 31, v2
	v_lshrrev_b32_e32 v3, 22, v3
	v_add_u32_e32 v3, v2, v3
	v_ashrrev_i32_e32 v13, 10, v3
	v_mul_i32_i24_e32 v3, 0x400, v13
	v_sub_u32_e32 v2, v2, v3
	v_lshrrev_b32_e32 v3, 4, v2
	s_lshl_b64 s[10:11], s[8:9], 19
	v_readlane_b32 s0, v253, 58
	v_bitop3_b32 v2, v3, v2, 32 bitop3:0x6c
	s_add_u32 s0, s0, s10
	v_readlane_b32 s1, v253, 59
	v_ashrrev_i32_e32 v4, 31, v2
	s_addc_u32 s1, s1, s11
	s_ashr_i32 s7, s6, 31
	v_lshrrev_b32_e32 v4, 26, v4
	s_lshl_b64 s[12:13], s[6:7], 19
	v_lshlrev_b32_e32 v3, 3, v13
	v_add_u32_e32 v4, v2, v4
	s_add_u32 s14, s18, s12
	v_and_b32_e32 v3, 0x3ffff0, v3
	v_ashrrev_i32_e32 v15, 6, v4
	v_lshlrev_b32_e32 v5, 5, v13
	v_and_b32_e32 v4, 0xc0, v4
	s_addc_u32 s15, s19, s13
	v_add_u32_e32 v3, v15, v3
	v_and_b32_e32 v16, 32, v5
	v_sub_u32_e32 v2, v2, v4
	v_lshl_or_b32 v0, v0, 10, v12
	s_add_u32 s64, s14, 0x480000
	v_ashrrev_i16_sdwa v17, v190, sext(v2) dst_sel:DWORD dst_unused:UNUSED_PAD src0_sel:DWORD src1_sel:BYTE_0
	v_add_u32_sdwa v0, v0, sext(v14) dst_sel:DWORD dst_unused:UNUSED_PAD src0_sel:DWORD src1_sel:WORD_0
	v_lshl_or_b32 v2, v3, 10, v16
	v_add_u32_e32 v144, s33, v18
	s_addc_u32 s65, s15, 0
	v_add_u32_sdwa v130, v2, sext(v17) dst_sel:DWORD dst_unused:UNUSED_PAD src0_sel:DWORD src1_sel:WORD_0
	v_lshlrev_b64 v[20:21], 1, v[0:1]
	v_readfirstlane_b32 s58, v144
	v_mov_b32_e32 v131, v1
	v_add_u32_e32 v145, 0x2000, v144
	v_lshl_add_u64 v[2:3], s[64:65], 0, v[20:21]
	s_mov_b32 m0, s58
	v_lshlrev_b64 v[22:23], 1, v[130:131]
	v_readfirstlane_b32 s58, v145
	v_add_u32_e32 v146, 16, v18
	v_readfirstlane_b32 s7, v140
	global_load_lds_dwordx4 v[2:3], off
	v_lshl_add_u64 v[6:7], s[64:65], 0, v[22:23]
	s_mov_b32 m0, s58
	v_readfirstlane_b32 s58, v146
	v_add_u32_e32 v147, 0x2000, v146
	s_ashr_i32 s31, s7, 8
	global_load_lds_dwordx4 v[6:7], off
	v_lshl_add_u64 v[8:9], s[0:1], 0, v[20:21]
	s_mov_b32 m0, s58
	v_readfirstlane_b32 s58, v147
	global_load_lds_dwordx4 v[8:9], off
	s_mov_b32 m0, s58
	s_add_u32 s58, s14, 0x4c0000
	v_add_u32_e32 v149, s38, v18
	v_lshl_add_u64 v[4:5], s[0:1], 0, v[22:23]
	s_addc_u32 s59, s15, 0
	v_readfirstlane_b32 s14, v149
	global_load_lds_dwordx4 v[4:5], off
	v_lshl_add_u64 v[24:25], s[58:59], 0, v[20:21]
	s_mov_b32 m0, s14
	v_add_u32_e32 v150, 0x2000, v149
	global_load_lds_dwordx4 v[24:25], off
	v_lshl_add_u64 v[24:25], s[58:59], 0, v[22:23]
	v_readfirstlane_b32 s14, v150
	s_add_u32 s58, s0, 0x40000
	v_add_u32_e32 v151, 0x4000, v146
	s_mov_b32 m0, s14
	s_addc_u32 s59, s1, 0
	v_readfirstlane_b32 s14, v151
	v_add_u32_e32 v152, 0x6000, v146
	global_load_lds_dwordx4 v[24:25], off
	v_lshl_add_u64 v[20:21], s[58:59], 0, v[20:21]
	s_mov_b32 m0, s14
	v_readfirstlane_b32 s14, v152
	global_load_lds_dwordx4 v[20:21], off
	v_lshl_add_u64 v[20:21], s[58:59], 0, v[22:23]
	s_mov_b32 m0, s14
	s_cmp_lg_u32 s31, 1
	global_load_lds_dwordx4 v[20:21], off
	v_mov_b32_e32 v26, 0
	v_mov_b32_e32 v27, 0
	v_mov_b32_e32 v28, 0
	v_mov_b32_e32 v29, 0
	v_mov_b32_e32 v30, 0
	v_mov_b32_e32 v31, 0
	v_mov_b32_e32 v32, 0
	v_mov_b32_e32 v33, 0
	v_mov_b32_e32 v34, 0
	v_mov_b32_e32 v35, 0
	v_mov_b32_e32 v36, 0
	v_mov_b32_e32 v37, 0
	v_mov_b32_e32 v38, 0
	v_mov_b32_e32 v39, 0
	v_mov_b32_e32 v40, 0
	v_mov_b32_e32 v41, 0
	v_mov_b32_e32 v42, 0
	v_mov_b32_e32 v43, 0
	v_mov_b32_e32 v44, 0
	v_mov_b32_e32 v45, 0
	v_mov_b32_e32 v46, 0
	v_mov_b32_e32 v47, 0
	v_mov_b32_e32 v48, 0
	v_mov_b32_e32 v49, 0
	v_mov_b32_e32 v50, 0
	v_mov_b32_e32 v51, 0
	v_mov_b32_e32 v52, 0
	v_mov_b32_e32 v53, 0
	v_mov_b32_e32 v54, 0
	v_mov_b32_e32 v55, 0
	v_mov_b32_e32 v56, 0
	v_mov_b32_e32 v57, 0
	v_mov_b32_e32 v58, 0
	v_mov_b32_e32 v59, 0
	v_mov_b32_e32 v60, 0
	v_mov_b32_e32 v61, 0
	v_mov_b32_e32 v62, 0
	v_mov_b32_e32 v63, 0
	v_mov_b32_e32 v64, 0
	v_mov_b32_e32 v65, 0
	v_mov_b32_e32 v66, 0
	v_mov_b32_e32 v67, 0
	v_mov_b32_e32 v68, 0
	v_mov_b32_e32 v69, 0
	v_mov_b32_e32 v70, 0
	v_mov_b32_e32 v71, 0
	v_mov_b32_e32 v72, 0
	v_mov_b32_e32 v73, 0
	v_mov_b32_e32 v74, 0
	v_mov_b32_e32 v75, 0
	v_mov_b32_e32 v76, 0
	v_mov_b32_e32 v77, 0
	v_mov_b32_e32 v78, 0
	v_mov_b32_e32 v79, 0
	v_mov_b32_e32 v80, 0
	v_mov_b32_e32 v81, 0
	v_mov_b32_e32 v82, 0
	v_mov_b32_e32 v83, 0
	v_mov_b32_e32 v84, 0
	v_mov_b32_e32 v85, 0
	v_mov_b32_e32 v86, 0
	v_mov_b32_e32 v87, 0
	v_mov_b32_e32 v88, 0
	v_mov_b32_e32 v89, 0
	v_mov_b32_e32 v90, 0
	v_mov_b32_e32 v91, 0
	v_mov_b32_e32 v92, 0
	v_mov_b32_e32 v93, 0
	v_mov_b32_e32 v94, 0
	v_mov_b32_e32 v95, 0
	v_mov_b32_e32 v96, 0
	v_mov_b32_e32 v97, 0
	v_mov_b32_e32 v98, 0
	v_mov_b32_e32 v99, 0
	v_mov_b32_e32 v100, 0
	v_mov_b32_e32 v101, 0
	v_mov_b32_e32 v102, 0
	v_mov_b32_e32 v103, 0
	v_mov_b32_e32 v104, 0
	v_mov_b32_e32 v105, 0
	v_mov_b32_e32 v106, 0
	v_mov_b32_e32 v107, 0
	v_mov_b32_e32 v108, 0
	v_mov_b32_e32 v109, 0
	v_mov_b32_e32 v110, 0
	v_mov_b32_e32 v111, 0
	v_mov_b32_e32 v112, 0
	v_mov_b32_e32 v113, 0
	v_mov_b32_e32 v114, 0
	v_mov_b32_e32 v115, 0
	v_mov_b32_e32 v116, 0
	v_mov_b32_e32 v117, 0
	v_mov_b32_e32 v118, 0
	v_mov_b32_e32 v119, 0
	v_mov_b32_e32 v120, 0
	v_mov_b32_e32 v121, 0
	v_mov_b32_e32 v122, 0
	v_mov_b32_e32 v123, 0
	v_mov_b32_e32 v124, 0
	v_mov_b32_e32 v125, 0
	v_mov_b32_e32 v126, 0
	v_mov_b32_e32 v127, 0
	v_mov_b32_e32 v128, 0
	v_mov_b32_e32 v129, 0
	s_cbranch_scc1 .LBB0_538
	s_barrier
; #define WAIT_V(n) asm volatile("s_waitcnt vmcnt(" #n ")" ::: "memory")
; #define BAR __builtin_amdgcn_s_barrier()
; template <bool PRE, bool NEXT> ...
;     ...
;   const int wid = __builtin_amdgcn_readfirstlane(tid >> 6), lane = tid & 63, wr = wid >> 2, wc = wid & 3, fr = lane & 15, fq = lane >> 4;
;   unsigned off0_A, off1_A, off0_Bt, off1_Bt;
;   { int r0, c0, r1, c1; stage_rc(tid * 16, r0, c0); stage_rc(tid * 16 + 8192, r1, c1);
;     off0_A = r0 * lda + c0; off1_A = r1 * lda + c1; off0_Bt = r0 * ldb + c0; off1_Bt = r1 * ldb + c1; }
;   bf16x8 At[4][2], B0[2][2], B1[2][2];
;   const int nt = K / BK;
;   if constexpr (!PRE) {
;     STAGE(SB(0, 0), Bt, ldb, 0, 0); STAGE(SA(0, 0), A, lda, 0, 0);
;     STAGE(SB(0, 1), Bt, ldb, HALF, 0); STAGE(SA(0, 1), A, lda, HALF, 0);
;   }
;   if (wr == 1) BAR;
;   if constexpr (PRE) WAIT_V(0); else WAIT_V(4);
;   BAR;
;   STAGE(SB(1, 0), Bt, ldb, 0, 1); STAGE(SA(1, 0), A, lda, 0, 1); STAGE(SB(1, 1), Bt, ldb, HALF, 1);
;   WAIT_V(6); BAR;
; template <int MODE, bool PRE = false, bool NEXT = false> ...
;     ...
; #pragma unroll
;   for (int ai = 0; ai < 2; ++ai)
; #pragma unroll
;     for (int bj = 0; bj < 2; ++bj)
; #pragma unroll
;       for (int m = 0; m < 4; ++m)
; #pragma unroll
;         for (int n = 0; n < 2; ++n) acc[ai][bj][m][n] = f32x4{0.f, 0.f, 0.f, 0.f};
.LBB0_538:
	v_readlane_b32 s15, v252, 10
	s_mov_b64 s[58:59], 0x80
	v_lshl_add_u64 v[2:3], v[2:3], 0, s[58:59]
	v_add_u32_e32 v153, s15, v18
	v_add_u32_e32 v154, 0x2000, v153
	v_readfirstlane_b32 s14, v153
	s_mov_b32 m0, s14
	v_readfirstlane_b32 s14, v154
	v_add_u32_e32 v155, 0x8000, v146
	s_waitcnt vmcnt(4)
	s_barrier
	global_load_lds_dwordx4 v[2:3], off
	v_lshl_add_u64 v[2:3], v[6:7], 0, s[58:59]
	s_mov_b32 m0, s14
	v_readfirstlane_b32 s14, v155
	global_load_lds_dwordx4 v[2:3], off
	v_lshl_add_u64 v[2:3], v[8:9], 0, s[58:59]
	s_mov_b32 m0, s14
	v_add_u32_e32 v156, 0xa000, v146
	v_readlane_b32 s22, v252, 11
	global_load_lds_dwordx4 v[2:3], off
	v_lshl_add_u64 v[2:3], v[4:5], 0, s[58:59]
	v_readfirstlane_b32 s14, v156
	s_add_u32 s58, s64, 0x40080
	v_add_u32_e32 v157, s22, v18
	s_mov_b32 m0, s14
	s_addc_u32 s59, s65, 0
	v_readfirstlane_b32 s14, v157
	v_add_u32_e32 v158, 0x2000, v157
	global_load_lds_dwordx4 v[2:3], off
	v_lshl_add_u64 v[2:3], v[0:1], 1, s[58:59]
	s_mov_b32 m0, s14
	v_readfirstlane_b32 s14, v158
	global_load_lds_dwordx4 v[2:3], off
	v_lshl_add_u64 v[2:3], v[130:131], 1, s[58:59]
	s_mov_b32 m0, s14
	v_and_b32_e32 v141, 15, v140
	global_load_lds_dwordx4 v[2:3], off
	v_lshlrev_b32_e32 v3, 2, v140
	v_and_b32_e32 v19, 48, v140
	v_lshlrev_b32_e32 v2, 6, v141
	v_and_b32_e32 v3, 32, v3
	v_bitop3_b32 v2, v2, v3, v19 bitop3:0x36
	v_add_u32_e32 v6, s33, v2
	v_add_u32_e32 v7, s38, v2
	v_add_u32_e32 v8, s15, v2
	v_add_u32_e32 v9, s22, v2
	v_add_u32_e32 v18, 16, v2
	v_lshlrev_b32_e32 v2, 6, v140
	s_movk_i32 s22, 0x3c0
	v_and_or_b32 v2, v2, s22, v19
	v_xad_u32 v160, v2, v3, 16
	v_lshlrev_b32_e32 v2, 13, v10
	v_and_b32_e32 v2, 0xffffc000, v2
	v_lshlrev_b32_e32 v4, 13, v13
	s_lshl_b32 s14, s7, 6
	s_lshl_b32 s15, s31, 13
	v_lshl_add_u32 v2, v11, 10, v2
	v_and_b32_e32 v4, 0xffffc000, v4
	s_and_b32 s14, s14, 0x3000
	s_or_b32 s31, s15, 0x800
	s_or_b32 s58, s15, 0x1000
	s_or_b32 s59, s15, 0x1800
	v_or_b32_e32 v2, v2, v12
	v_lshl_add_u32 v4, v15, 10, v4
	s_add_u32 s12, s17, s12
	v_add_u32_sdwa v2, v2, sext(v14) dst_sel:DWORD dst_unused:UNUSED_PAD src0_sel:DWORD src1_sel:WORD_0
	v_mov_b32_e32 v3, v1
	v_or_b32_e32 v4, v4, v16
	s_waitcnt vmcnt(6)
	s_addc_u32 s13, 0, s13
	v_lshlrev_b64 v[2:3], 1, v[2:3]
	v_add_u32_sdwa v4, v4, sext(v17) dst_sel:DWORD dst_unused:UNUSED_PAD src0_sel:DWORD src1_sel:WORD_0
	v_mov_b32_e32 v5, v1
	v_lshl_add_u64 v[132:133], s[12:13], 0, v[2:3]
	v_lshlrev_b64 v[4:5], 1, v[4:5]
	v_lshl_add_u64 v[136:137], s[10:11], 0, v[2:3]
	v_mov_b32_e32 v2, 0
	v_lshl_add_u64 v[134:135], s[12:13], 0, v[4:5]
	v_lshl_add_u64 v[138:139], s[10:11], 0, v[4:5]
	s_mov_b32 s10, -2
	v_add_u32_e32 v161, s14, v6
	v_add_u32_e32 v142, s15, v18
	v_add_u32_e32 v159, s14, v7
	v_add_u32_e32 v148, s14, v8
	v_add_u32_e32 v143, s14, v9
	v_mov_b32_e32 v3, v2
	v_mov_b32_e32 v4, v2
	v_mov_b32_e32 v5, v2
	v_mov_b32_e32 v6, v2
	v_mov_b32_e32 v7, v2
	v_mov_b32_e32 v8, v2
	v_mov_b32_e32 v9, v2
	v_mov_b32_e32 v10, v2
	v_mov_b32_e32 v11, v2
	v_mov_b32_e32 v12, v2
	v_mov_b32_e32 v13, v2
	v_mov_b32_e32 v14, v2
	v_mov_b32_e32 v15, v2
	v_mov_b32_e32 v16, v2
	v_mov_b32_e32 v17, v2
	v_mov_b32_e32 v18, v2
	v_mov_b32_e32 v19, v2
	v_mov_b32_e32 v20, v2
	v_mov_b32_e32 v21, v2
	v_mov_b32_e32 v22, v2
	v_mov_b32_e32 v23, v2
	v_mov_b32_e32 v24, v2
	v_mov_b32_e32 v25, v2
	s_waitcnt vmcnt(0)
	s_mov_b64 s[12:13], 0x480100
	s_mov_b64 s[14:15], 0x4c0100
	s_mov_b64 s[60:61], 0x480180
	s_mov_b64 s[64:65], 0x4c0180
	s_barrier

; #define BAR __builtin_amdgcn_s_barrier()
; template <bool PRE, bool NEXT> ...
;     ...
;   const int wid = __builtin_amdgcn_readfirstlane(tid >> 6), lane = tid & 63, wr = wid >> 2, wc = wid & 3, fr = lane & 15, fq = lane >> 4;
;   unsigned off0_A, off1_A, off0_Bt, off1_Bt;
;   { int r0, c0, r1, c1; stage_rc(tid * 16, r0, c0); stage_rc(tid * 16 + 8192, r1, c1);
;     off0_A = r0 * lda + c0; off1_A = r1 * lda + c1; off0_Bt = r0 * ldb + c0; off1_Bt = r1 * ldb + c1; }
;   bf16x8 At[4][2], B0[2][2], B1[2][2];
;   const int nt = K / BK;
;   if constexpr (!PRE) {
;     STAGE(SB(0, 0), Bt, ldb, 0, 0); STAGE(SA(0, 0), A, lda, 0, 0);
;     STAGE(SB(0, 1), Bt, ldb, HALF, 0); STAGE(SA(0, 1), A, lda, HALF, 0);
;   }
;   if (wr == 1) BAR;
; template <int MODE, bool PRE = false, bool NEXT = false> ...
;     ...
; #pragma unroll
;   for (int ai = 0; ai < 2; ++ai)
; #pragma unroll
;     for (int bj = 0; bj < 2; ++bj)
; #pragma unroll
;       for (int m = 0; m < 4; ++m)
; #pragma unroll
;         for (int n = 0; n < 2; ++n) acc[ai][bj][m][n] = f32x4{0.f, 0.f, 0.f, 0.f};
.LBB0_581:
	v_mov_b32_e32 v130, v181
	s_barrier
	s_ashr_i32 s11, s10, 31
	v_ashrrev_i32_e32 v131, 31, v130
	v_lshrrev_b32_e32 v0, 26, v131
	v_add_u32_e32 v0, v130, v0
	v_ashrrev_i32_e32 v10, 6, v0
	v_bfe_i32 v0, v130, 27, 1
	v_lshlrev_b32_e32 v18, 4, v130
	v_lshrrev_b32_e32 v0, 22, v0
	v_add_u32_e32 v0, v18, v0
	v_and_b32_e32 v0, 0xfffffc00, v0
	v_sub_u32_e32 v0, v18, v0
	v_lshrrev_b32_e32 v2, 4, v0
	v_bitop3_b32 v2, v2, v0, 32 bitop3:0x6c
	v_ashrrev_i32_e32 v0, 31, v0
	v_lshrrev_b32_e32 v0, 26, v0
	v_lshlrev_b32_e32 v3, 3, v10
	v_add_u32_e32 v0, v2, v0
	v_and_b32_e32 v3, 0x3ffff0, v3
	v_ashrrev_i32_e32 v11, 6, v0
	v_add_u32_e32 v0, v11, v3
	v_lshlrev_b32_e32 v3, 5, v10
	v_and_b32_e32 v12, 32, v3
	v_mul_i32_i24_e32 v3, 64, v11
	v_sub_u32_e32 v2, v2, v3
	v_ashrrev_i16_sdwa v14, v190, sext(v2) dst_sel:DWORD dst_unused:UNUSED_PAD src0_sel:DWORD src1_sel:BYTE_0
	v_add_u32_e32 v2, 0x2000, v18
	v_ashrrev_i32_e32 v3, 31, v2
	v_lshrrev_b32_e32 v3, 22, v3
	v_add_u32_e32 v3, v2, v3
	v_ashrrev_i32_e32 v13, 10, v3
	v_mul_i32_i24_e32 v3, 0x400, v13
	v_sub_u32_e32 v2, v2, v3
	v_lshrrev_b32_e32 v3, 4, v2
	v_bitop3_b32 v2, v3, v2, 32 bitop3:0x6c
	v_ashrrev_i32_e32 v4, 31, v2
	s_lshl_b64 s[0:1], s[10:11], 19
	v_readlane_b32 s7, v254, 6
	v_lshrrev_b32_e32 v4, 26, v4
	s_add_u32 s12, s7, s0
	v_readlane_b32 s7, v254, 7
	v_lshlrev_b32_e32 v3, 3, v13
	v_add_u32_e32 v4, v2, v4
	s_addc_u32 s13, s7, s1
	s_ashr_i32 s7, s6, 31
	v_and_b32_e32 v3, 0x3ffff0, v3
	v_ashrrev_i32_e32 v15, 6, v4
	v_lshlrev_b32_e32 v5, 5, v13
	v_and_b32_e32 v4, 0xc0, v4
	s_lshl_b64 s[8:9], s[6:7], 19
	v_readlane_b32 s14, v252, 47
	v_add_u32_e32 v3, v15, v3
	v_and_b32_e32 v16, 32, v5
	v_sub_u32_e32 v2, v2, v4
	v_lshl_or_b32 v0, v0, 10, v12
	s_add_u32 vcc_lo, s14, s8
	v_readlane_b32 s14, v252, 48
	v_ashrrev_i16_sdwa v17, v190, sext(v2) dst_sel:DWORD dst_unused:UNUSED_PAD src0_sel:DWORD src1_sel:BYTE_0
	v_add_u32_sdwa v0, v0, sext(v14) dst_sel:DWORD dst_unused:UNUSED_PAD src0_sel:DWORD src1_sel:WORD_0
	v_lshl_or_b32 v2, v3, 10, v16
	v_add_u32_e32 v143, s33, v18
	s_addc_u32 vcc_hi, s14, s9
	v_add_u32_sdwa v132, v2, sext(v17) dst_sel:DWORD dst_unused:UNUSED_PAD src0_sel:DWORD src1_sel:WORD_0
	v_lshlrev_b64 v[20:21], 1, v[0:1]
	v_readfirstlane_b32 s14, v143
	v_mov_b32_e32 v133, v1
	v_add_u32_e32 v144, 0x2000, v143
	v_readfirstlane_b32 s31, v130
	v_lshl_add_u64 v[2:3], vcc, 0, v[20:21]
	s_mov_b32 m0, s14
	v_lshlrev_b64 v[22:23], 1, v[132:133]
	v_readfirstlane_b32 s14, v144
	v_add_u32_e32 v145, 16, v18
	s_ashr_i32 s58, s31, 8
	global_load_lds_dwordx4 v[2:3], off
	v_lshl_add_u64 v[6:7], vcc, 0, v[22:23]
	s_mov_b32 m0, s14
	v_readfirstlane_b32 s14, v145
	v_add_u32_e32 v146, 0x2000, v145
	global_load_lds_dwordx4 v[6:7], off
	v_lshl_add_u64 v[8:9], s[12:13], 0, v[20:21]
	s_mov_b32 m0, s14
	v_readfirstlane_b32 s14, v146
	s_add_u32 s60, vcc_lo, 0x40000
	v_add_u32_e32 v147, s38, v18
	global_load_lds_dwordx4 v[8:9], off
	v_lshl_add_u64 v[4:5], s[12:13], 0, v[22:23]
	s_mov_b32 m0, s14
	s_addc_u32 s61, vcc_hi, 0
	v_readfirstlane_b32 s14, v147
	global_load_lds_dwordx4 v[4:5], off
	v_lshl_add_u64 v[24:25], s[60:61], 0, v[20:21]
	s_mov_b32 m0, s14
	v_add_u32_e32 v148, 0x2000, v147
	global_load_lds_dwordx4 v[24:25], off
	v_lshl_add_u64 v[24:25], s[60:61], 0, v[22:23]
	v_readfirstlane_b32 s14, v148
	s_add_u32 s60, s12, 0x40000
	v_add_u32_e32 v149, 0x4000, v145
	s_mov_b32 m0, s14
	s_addc_u32 s61, s13, 0
	v_readfirstlane_b32 s14, v149
	v_add_u32_e32 v151, 0x6000, v145
	global_load_lds_dwordx4 v[24:25], off
	v_lshl_add_u64 v[20:21], s[60:61], 0, v[20:21]
	s_mov_b32 m0, s14
	v_readfirstlane_b32 s14, v151
	global_load_lds_dwordx4 v[20:21], off
	v_lshl_add_u64 v[20:21], s[60:61], 0, v[22:23]
	s_mov_b32 m0, s14
	s_cmp_lg_u32 s58, 1
	global_load_lds_dwordx4 v[20:21], off
	v_mov_b32_e32 v26, 0
	v_mov_b32_e32 v27, 0
	v_mov_b32_e32 v28, 0
	v_mov_b32_e32 v29, 0
	v_mov_b32_e32 v30, 0
	v_mov_b32_e32 v31, 0
	v_mov_b32_e32 v32, 0
	v_mov_b32_e32 v33, 0
	v_mov_b32_e32 v34, 0
	v_mov_b32_e32 v35, 0
	v_mov_b32_e32 v36, 0
	v_mov_b32_e32 v37, 0
	v_mov_b32_e32 v38, 0
	v_mov_b32_e32 v39, 0
	v_mov_b32_e32 v40, 0
	v_mov_b32_e32 v41, 0
	v_mov_b32_e32 v42, 0
	v_mov_b32_e32 v43, 0
	v_mov_b32_e32 v44, 0
	v_mov_b32_e32 v45, 0
	v_mov_b32_e32 v46, 0
	v_mov_b32_e32 v47, 0
	v_mov_b32_e32 v48, 0
	v_mov_b32_e32 v49, 0
	v_mov_b32_e32 v50, 0
	v_mov_b32_e32 v51, 0
	v_mov_b32_e32 v52, 0
	v_mov_b32_e32 v53, 0
	v_mov_b32_e32 v54, 0
	v_mov_b32_e32 v55, 0
	v_mov_b32_e32 v56, 0
	v_mov_b32_e32 v57, 0
	v_mov_b32_e32 v58, 0
	v_mov_b32_e32 v59, 0
	v_mov_b32_e32 v60, 0
	v_mov_b32_e32 v61, 0
	v_mov_b32_e32 v62, 0
	v_mov_b32_e32 v63, 0
	v_mov_b32_e32 v64, 0
	v_mov_b32_e32 v65, 0
	v_mov_b32_e32 v66, 0
	v_mov_b32_e32 v67, 0
	v_mov_b32_e32 v68, 0
	v_mov_b32_e32 v69, 0
	v_mov_b32_e32 v70, 0
	v_mov_b32_e32 v71, 0
	v_mov_b32_e32 v72, 0
	v_mov_b32_e32 v73, 0
	v_mov_b32_e32 v74, 0
	v_mov_b32_e32 v75, 0
	v_mov_b32_e32 v76, 0
	v_mov_b32_e32 v77, 0
	v_mov_b32_e32 v78, 0
	v_mov_b32_e32 v79, 0
	v_mov_b32_e32 v80, 0
	v_mov_b32_e32 v81, 0
	v_mov_b32_e32 v82, 0
	v_mov_b32_e32 v83, 0
	v_mov_b32_e32 v84, 0
	v_mov_b32_e32 v85, 0
	v_mov_b32_e32 v86, 0
	v_mov_b32_e32 v87, 0
	v_mov_b32_e32 v88, 0
	v_mov_b32_e32 v89, 0
	v_mov_b32_e32 v90, 0
	v_mov_b32_e32 v91, 0
	v_mov_b32_e32 v92, 0
	v_mov_b32_e32 v93, 0
	v_mov_b32_e32 v94, 0
	v_mov_b32_e32 v95, 0
	v_mov_b32_e32 v96, 0
	v_mov_b32_e32 v97, 0
	v_mov_b32_e32 v98, 0
	v_mov_b32_e32 v99, 0
	v_mov_b32_e32 v100, 0
	v_mov_b32_e32 v101, 0
	v_mov_b32_e32 v102, 0
	v_mov_b32_e32 v103, 0
	v_mov_b32_e32 v104, 0
	v_mov_b32_e32 v105, 0
	v_mov_b32_e32 v106, 0
	v_mov_b32_e32 v107, 0
	v_mov_b32_e32 v108, 0
	v_mov_b32_e32 v109, 0
	v_mov_b32_e32 v110, 0
	v_mov_b32_e32 v111, 0
	v_mov_b32_e32 v112, 0
	v_mov_b32_e32 v113, 0
	v_mov_b32_e32 v114, 0
	v_mov_b32_e32 v115, 0
	v_mov_b32_e32 v116, 0
	v_mov_b32_e32 v117, 0
	v_mov_b32_e32 v118, 0
	v_mov_b32_e32 v119, 0
	v_mov_b32_e32 v120, 0
	v_mov_b32_e32 v121, 0
	v_mov_b32_e32 v122, 0
	v_mov_b32_e32 v123, 0
	v_mov_b32_e32 v124, 0
	v_mov_b32_e32 v125, 0
	v_mov_b32_e32 v126, 0
	v_mov_b32_e32 v127, 0
	v_mov_b32_e32 v128, 0
	v_mov_b32_e32 v129, 0
	s_cbranch_scc1 .LBB0_583
	s_barrier
; #define WAIT_V(n) asm volatile("s_waitcnt vmcnt(" #n ")" ::: "memory")
; #define BAR __builtin_amdgcn_s_barrier()
; template <bool PRE, bool NEXT> ...
;     ...
;   const int wid = __builtin_amdgcn_readfirstlane(tid >> 6), lane = tid & 63, wr = wid >> 2, wc = wid & 3, fr = lane & 15, fq = lane >> 4;
;   unsigned off0_A, off1_A, off0_Bt, off1_Bt;
;   { int r0, c0, r1, c1; stage_rc(tid * 16, r0, c0); stage_rc(tid * 16 + 8192, r1, c1);
;     off0_A = r0 * lda + c0; off1_A = r1 * lda + c1; off0_Bt = r0 * ldb + c0; off1_Bt = r1 * ldb + c1; }
;   bf16x8 At[4][2], B0[2][2], B1[2][2];
;   const int nt = K / BK;
;   if constexpr (!PRE) {
;     STAGE(SB(0, 0), Bt, ldb, 0, 0); STAGE(SA(0, 0), A, lda, 0, 0);
;     STAGE(SB(0, 1), Bt, ldb, HALF, 0); STAGE(SA(0, 1), A, lda, HALF, 0);
;   }
;   if (wr == 1) BAR;
;   if constexpr (PRE) WAIT_V(0); else WAIT_V(4);
;   BAR;
;   STAGE(SB(1, 0), Bt, ldb, 0, 1); STAGE(SA(1, 0), A, lda, 0, 1); STAGE(SB(1, 1), Bt, ldb, HALF, 1);
;   WAIT_V(6); BAR;
; template <int MODE, bool PRE = false, bool NEXT = false> ...
;     ...
; #pragma unroll
;   for (int ai = 0; ai < 2; ++ai)
; #pragma unroll
;     for (int bj = 0; bj < 2; ++bj)
; #pragma unroll
;       for (int m = 0; m < 4; ++m)
; #pragma unroll
;         for (int n = 0; n < 2; ++n) acc[ai][bj][m][n] = f32x4{0.f, 0.f, 0.f, 0.f};
.LBB0_583:
	s_lshl_b64 s[80:81], s[10:11], 18
	v_readlane_b32 s11, v252, 10
	s_lshl_b64 s[64:65], s[6:7], 18
	s_mov_b64 s[14:15], 0x80
	v_add_u32_e32 v155, s11, v18
	v_add_u32_e32 v156, 0x2000, v155
	v_readfirstlane_b32 s7, v155
	v_lshl_add_u64 v[2:3], v[2:3], 0, s[14:15]
	s_mov_b32 m0, s7
	v_readfirstlane_b32 s7, v156
	v_add_u32_e32 v157, 0x8000, v145
	s_waitcnt vmcnt(4)
	s_barrier
	global_load_lds_dwordx4 v[2:3], off
	v_lshl_add_u64 v[2:3], v[6:7], 0, s[14:15]
	s_mov_b32 m0, s7
	v_readfirstlane_b32 s7, v157
	global_load_lds_dwordx4 v[2:3], off
	v_lshl_add_u64 v[2:3], v[8:9], 0, s[14:15]
	s_mov_b32 m0, s7
	v_add_u32_e32 v158, 0xa000, v145
	global_load_lds_dwordx4 v[2:3], off
	v_lshl_add_u64 v[2:3], v[4:5], 0, s[14:15]
	v_readlane_b32 s14, v252, 11
	v_readfirstlane_b32 s7, v158
	s_add_u32 s60, vcc_lo, 0x40080
	v_add_u32_e32 v159, s14, v18
	s_mov_b32 m0, s7
	s_addc_u32 s61, vcc_hi, 0
	v_readfirstlane_b32 s7, v159
	v_add_u32_e32 v161, 0x2000, v159
	global_load_lds_dwordx4 v[2:3], off
	v_lshl_add_u64 v[2:3], v[0:1], 1, s[60:61]
	s_mov_b32 m0, s7
	v_readfirstlane_b32 s7, v161
	global_load_lds_dwordx4 v[2:3], off
	v_lshl_add_u64 v[2:3], v[132:133], 1, s[60:61]
	s_mov_b32 m0, s7
	v_and_b32_e32 v150, 15, v130
	global_load_lds_dwordx4 v[2:3], off
	v_lshlrev_b32_e32 v3, 2, v130
	v_and_b32_e32 v19, 48, v130
	v_lshlrev_b32_e32 v2, 6, v150
	v_and_b32_e32 v3, 32, v3
	v_bitop3_b32 v2, v2, v3, v19 bitop3:0x36
	s_lshl_b32 s7, s31, 6
	v_add_u32_e32 v6, s33, v2
	v_add_u32_e32 v7, s38, v2
	v_add_u32_e32 v8, s11, v2
	v_add_u32_e32 v9, s14, v2
	s_and_b32 s14, s7, 0x3000
	v_add_u32_e32 v18, 16, v2
	v_lshlrev_b32_e32 v2, 6, v130
	s_movk_i32 s7, 0x3c0
	v_and_or_b32 v2, v2, s7, v19
	v_xad_u32 v162, v2, v3, 16
	v_lshlrev_b32_e32 v2, 13, v10
	v_and_b32_e32 v2, 0xffffc000, v2
	v_lshlrev_b32_e32 v4, 13, v13
	s_lshl_b32 s15, s58, 13
	v_lshl_add_u32 v2, v11, 10, v2
	v_and_b32_e32 v4, 0xffffc000, v4
	s_or_b32 s7, s15, 0x800
	s_or_b32 s11, s15, 0x1000
	s_or_b32 s58, s15, 0x1800
	v_or_b32_e32 v2, v2, v12
	v_lshl_add_u32 v4, v15, 10, v4
	s_add_u32 s8, s17, s8
	v_add_u32_sdwa v2, v2, sext(v14) dst_sel:DWORD dst_unused:UNUSED_PAD src0_sel:DWORD src1_sel:WORD_0
	v_mov_b32_e32 v3, v1
	v_or_b32_e32 v4, v4, v16
	s_waitcnt vmcnt(6)
	s_addc_u32 s9, 0, s9
	v_lshlrev_b64 v[2:3], 1, v[2:3]
	v_add_u32_sdwa v4, v4, sext(v17) dst_sel:DWORD dst_unused:UNUSED_PAD src0_sel:DWORD src1_sel:WORD_0
	v_mov_b32_e32 v5, v1
	v_lshl_add_u64 v[134:135], s[8:9], 0, v[2:3]
	v_lshlrev_b64 v[4:5], 1, v[4:5]
	v_lshl_add_u64 v[138:139], s[0:1], 0, v[2:3]
	v_mov_b32_e32 v2, 0
	v_lshl_add_u64 v[136:137], s[8:9], 0, v[4:5]
	v_lshl_add_u64 v[140:141], s[0:1], 0, v[4:5]
	s_mov_b32 s59, -2
	v_add_u32_e32 v163, s14, v6
	v_add_u32_e32 v152, s15, v18
	v_add_u32_e32 v160, s14, v7
	v_add_u32_e32 v154, s14, v8
	v_add_u32_e32 v153, s14, v9
	v_mov_b32_e32 v3, v2
	v_mov_b32_e32 v4, v2
	v_mov_b32_e32 v5, v2
	v_mov_b32_e32 v6, v2
	v_mov_b32_e32 v7, v2
	v_mov_b32_e32 v8, v2
	v_mov_b32_e32 v9, v2
	v_mov_b32_e32 v10, v2
	v_mov_b32_e32 v11, v2
	v_mov_b32_e32 v12, v2
	v_mov_b32_e32 v13, v2
	v_mov_b32_e32 v14, v2
	v_mov_b32_e32 v15, v2
	v_mov_b32_e32 v16, v2
	v_mov_b32_e32 v17, v2
	v_mov_b32_e32 v18, v2
	v_mov_b32_e32 v19, v2
	v_mov_b32_e32 v20, v2
	v_mov_b32_e32 v21, v2
	v_mov_b32_e32 v22, v2
	v_mov_b32_e32 v23, v2
	v_mov_b32_e32 v24, v2
	v_mov_b32_e32 v25, v2
	s_waitcnt vmcnt(0)
	s_mov_b64 s[60:61], 0x35f71c80
	s_mov_b64 vcc, 0xca0100
	s_mov_b64 s[26:27], 0x35f31d00
	s_mov_b64 s[20:21], 0xce0100
	s_mov_b64 s[24:25], 0x35f71d00
	s_mov_b64 s[16:17], 0xca0180
	s_mov_b64 s[18:19], 0x35f31d80
	s_mov_b64 s[22:23], 0xce0180
	s_barrier

; #define BAR __builtin_amdgcn_s_barrier()
; template <bool PRE, bool NEXT> ...
;     ...
;   const int wid = __builtin_amdgcn_readfirstlane(tid >> 6), lane = tid & 63, wr = wid >> 2, wc = wid & 3, fr = lane & 15, fq = lane >> 4;
;   unsigned off0_A, off1_A, off0_Bt, off1_Bt;
;   { int r0, c0, r1, c1; stage_rc(tid * 16, r0, c0); stage_rc(tid * 16 + 8192, r1, c1);
;     off0_A = r0 * lda + c0; off1_A = r1 * lda + c1; off0_Bt = r0 * ldb + c0; off1_Bt = r1 * ldb + c1; }
;   bf16x8 At[4][2], B0[2][2], B1[2][2];
;   const int nt = K / BK;
;   if constexpr (!PRE) {
;     STAGE(SB(0, 0), Bt, ldb, 0, 0); STAGE(SA(0, 0), A, lda, 0, 0);
;     STAGE(SB(0, 1), Bt, ldb, HALF, 0); STAGE(SA(0, 1), A, lda, HALF, 0);
;   }
;   if (wr == 1) BAR;
; template <int MODE, bool PRE = false, bool NEXT = false> ...
;     ...
; #pragma unroll
;   for (int ai = 0; ai < 2; ++ai)
; #pragma unroll
;     for (int bj = 0; bj < 2; ++bj)
; #pragma unroll
;       for (int m = 0; m < 4; ++m)
; #pragma unroll
;         for (int n = 0; n < 2; ++n) acc[ai][bj][m][n] = f32x4{0.f, 0.f, 0.f, 0.f};
.LBB0_647:
	v_mov_b32_e32 v134, v181
	s_barrier
	s_ashr_i32 s7, s6, 31
	v_ashrrev_i32_e32 v135, 31, v134
	v_lshrrev_b32_e32 v0, 26, v135
	v_add_u32_e32 v0, v134, v0
	v_ashrrev_i32_e32 v10, 6, v0
	v_bfe_i32 v0, v134, 27, 1
	v_lshlrev_b32_e32 v18, 4, v134
	v_lshrrev_b32_e32 v0, 22, v0
	v_add_u32_e32 v0, v18, v0
	v_and_b32_e32 v0, 0xfffffc00, v0
	v_sub_u32_e32 v0, v18, v0
	v_lshrrev_b32_e32 v2, 4, v0
	v_bitop3_b32 v2, v2, v0, 32 bitop3:0x6c
	v_ashrrev_i32_e32 v0, 31, v0
	v_lshrrev_b32_e32 v0, 26, v0
	v_lshlrev_b32_e32 v3, 3, v10
	v_add_u32_e32 v0, v2, v0
	v_and_b32_e32 v3, 0x3ffff0, v3
	v_ashrrev_i32_e32 v11, 6, v0
	v_add_u32_e32 v0, v11, v3
	v_lshlrev_b32_e32 v3, 5, v10
	v_and_b32_e32 v12, 32, v3
	v_mul_i32_i24_e32 v3, 64, v11
	v_sub_u32_e32 v2, v2, v3
	v_ashrrev_i16_sdwa v14, v190, sext(v2) dst_sel:DWORD dst_unused:UNUSED_PAD src0_sel:DWORD src1_sel:BYTE_0
	v_add_u32_e32 v2, 0x2000, v18
	v_ashrrev_i32_e32 v3, 31, v2
	v_lshrrev_b32_e32 v3, 22, v3
	v_add_u32_e32 v3, v2, v3
	v_ashrrev_i32_e32 v13, 10, v3
	v_mul_i32_i24_e32 v3, 0x400, v13
	v_sub_u32_e32 v2, v2, v3
	v_lshrrev_b32_e32 v3, 4, v2
	v_bitop3_b32 v2, v3, v2, 32 bitop3:0x6c
	v_ashrrev_i32_e32 v4, 31, v2
	s_lshl_b64 s[12:13], s[6:7], 19
	v_readlane_b32 s1, v254, 43
	v_lshrrev_b32_e32 v4, 26, v4
	s_add_u32 s10, s1, s12
	v_readlane_b32 s1, v254, 44
	v_lshlrev_b32_e32 v3, 3, v13
	v_add_u32_e32 v4, v2, v4
	s_addc_u32 s11, s1, s13
	s_ashr_i32 s1, s0, 31
	v_and_b32_e32 v3, 0x3ffff0, v3
	v_ashrrev_i32_e32 v15, 6, v4
	v_lshlrev_b32_e32 v5, 5, v13
	v_and_b32_e32 v4, 0xc0, v4
	s_lshl_b64 s[64:65], s[0:1], 19
	v_add_u32_e32 v3, v15, v3
	v_and_b32_e32 v16, 32, v5
	v_sub_u32_e32 v2, v2, v4
	v_lshl_or_b32 v0, v0, 10, v12
	s_add_u32 s80, s20, s64
	v_ashrrev_i16_sdwa v17, v190, sext(v2) dst_sel:DWORD dst_unused:UNUSED_PAD src0_sel:DWORD src1_sel:BYTE_0
	v_add_u32_sdwa v0, v0, sext(v14) dst_sel:DWORD dst_unused:UNUSED_PAD src0_sel:DWORD src1_sel:WORD_0
	v_lshl_or_b32 v2, v3, 10, v16
	v_add_u32_e32 v145, s33, v18
	s_addc_u32 s81, s31, s65
	v_add_u32_sdwa v130, v2, sext(v17) dst_sel:DWORD dst_unused:UNUSED_PAD src0_sel:DWORD src1_sel:WORD_0
	v_lshlrev_b64 v[20:21], 1, v[0:1]
	v_readfirstlane_b32 s8, v145
	v_mov_b32_e32 v131, v1
	v_add_u32_e32 v146, 0x2000, v145
	v_lshl_add_u64 v[2:3], s[80:81], 0, v[20:21]
	s_mov_b32 m0, s8
	v_lshlrev_b64 v[22:23], 1, v[130:131]
	v_readfirstlane_b32 s8, v146
	v_add_u32_e32 v147, 16, v18
	v_readfirstlane_b32 s58, v134
	global_load_lds_dwordx4 v[2:3], off
	v_lshl_add_u64 v[6:7], s[80:81], 0, v[22:23]
	s_mov_b32 m0, s8
	v_readfirstlane_b32 s8, v147
	v_add_u32_e32 v148, 0x2000, v147
	s_ashr_i32 s59, s58, 8
	global_load_lds_dwordx4 v[6:7], off
	v_lshl_add_u64 v[8:9], s[10:11], 0, v[20:21]
	s_mov_b32 m0, s8
	v_readfirstlane_b32 s8, v148
	global_load_lds_dwordx4 v[8:9], off
	s_mov_b32 m0, s8
	s_add_u32 s8, s80, 0x40000
	v_add_u32_e32 v149, s38, v18
	v_lshl_add_u64 v[4:5], s[10:11], 0, v[22:23]
	s_addc_u32 s9, s81, 0
	v_readfirstlane_b32 s14, v149
	global_load_lds_dwordx4 v[4:5], off
	v_lshl_add_u64 v[24:25], s[8:9], 0, v[20:21]
	s_mov_b32 m0, s14
	v_add_u32_e32 v152, 0x2000, v149
	global_load_lds_dwordx4 v[24:25], off
	v_lshl_add_u64 v[24:25], s[8:9], 0, v[22:23]
	v_readfirstlane_b32 s8, v152
	s_mov_b32 m0, s8
	s_add_u32 s8, s10, 0x40000
	v_add_u32_e32 v153, 0x4000, v147
	s_addc_u32 s9, s11, 0
	v_readfirstlane_b32 s14, v153
	global_load_lds_dwordx4 v[24:25], off
	v_lshl_add_u64 v[20:21], s[8:9], 0, v[20:21]
	s_mov_b32 m0, s14
	v_add_u32_e32 v154, 0x6000, v147
	global_load_lds_dwordx4 v[20:21], off
	v_lshl_add_u64 v[20:21], s[8:9], 0, v[22:23]
	v_readfirstlane_b32 s8, v154
	s_mov_b32 m0, s8
	s_cmp_lg_u32 s59, 1
	global_load_lds_dwordx4 v[20:21], off
	v_mov_b32_e32 v26, 0
	v_mov_b32_e32 v27, 0
	v_mov_b32_e32 v28, 0
	v_mov_b32_e32 v29, 0
	v_mov_b32_e32 v30, 0
	v_mov_b32_e32 v31, 0
	v_mov_b32_e32 v32, 0
	v_mov_b32_e32 v33, 0
	v_mov_b32_e32 v34, 0
	v_mov_b32_e32 v35, 0
	v_mov_b32_e32 v36, 0
	v_mov_b32_e32 v37, 0
	v_mov_b32_e32 v38, 0
	v_mov_b32_e32 v39, 0
	v_mov_b32_e32 v40, 0
	v_mov_b32_e32 v41, 0
	v_mov_b32_e32 v42, 0
	v_mov_b32_e32 v43, 0
	v_mov_b32_e32 v44, 0
	v_mov_b32_e32 v45, 0
	v_mov_b32_e32 v46, 0
	v_mov_b32_e32 v47, 0
	v_mov_b32_e32 v48, 0
	v_mov_b32_e32 v49, 0
	v_mov_b32_e32 v50, 0
	v_mov_b32_e32 v51, 0
	v_mov_b32_e32 v52, 0
	v_mov_b32_e32 v53, 0
	v_mov_b32_e32 v54, 0
	v_mov_b32_e32 v55, 0
	v_mov_b32_e32 v56, 0
	v_mov_b32_e32 v57, 0
	v_mov_b32_e32 v58, 0
	v_mov_b32_e32 v59, 0
	v_mov_b32_e32 v60, 0
	v_mov_b32_e32 v61, 0
	v_mov_b32_e32 v62, 0
	v_mov_b32_e32 v63, 0
	v_mov_b32_e32 v64, 0
	v_mov_b32_e32 v65, 0
	v_mov_b32_e32 v66, 0
	v_mov_b32_e32 v67, 0
	v_mov_b32_e32 v68, 0
	v_mov_b32_e32 v69, 0
	v_mov_b32_e32 v70, 0
	v_mov_b32_e32 v71, 0
	v_mov_b32_e32 v72, 0
	v_mov_b32_e32 v73, 0
	v_mov_b32_e32 v74, 0
	v_mov_b32_e32 v75, 0
	v_mov_b32_e32 v76, 0
	v_mov_b32_e32 v77, 0
	v_mov_b32_e32 v78, 0
	v_mov_b32_e32 v79, 0
	v_mov_b32_e32 v80, 0
	v_mov_b32_e32 v81, 0
	v_mov_b32_e32 v82, 0
	v_mov_b32_e32 v83, 0
	v_mov_b32_e32 v84, 0
	v_mov_b32_e32 v85, 0
	v_mov_b32_e32 v86, 0
	v_mov_b32_e32 v87, 0
	v_mov_b32_e32 v88, 0
	v_mov_b32_e32 v89, 0
	v_mov_b32_e32 v90, 0
	v_mov_b32_e32 v91, 0
	v_mov_b32_e32 v92, 0
	v_mov_b32_e32 v93, 0
	v_mov_b32_e32 v94, 0
	v_mov_b32_e32 v95, 0
	v_mov_b32_e32 v96, 0
	v_mov_b32_e32 v97, 0
	v_mov_b32_e32 v98, 0
	v_mov_b32_e32 v99, 0
	v_mov_b32_e32 v100, 0
	v_mov_b32_e32 v101, 0
	v_mov_b32_e32 v102, 0
	v_mov_b32_e32 v103, 0
	v_mov_b32_e32 v104, 0
	v_mov_b32_e32 v105, 0
	v_mov_b32_e32 v106, 0
	v_mov_b32_e32 v107, 0
	v_mov_b32_e32 v108, 0
	v_mov_b32_e32 v109, 0
	v_mov_b32_e32 v110, 0
	v_mov_b32_e32 v111, 0
	v_mov_b32_e32 v112, 0
	v_mov_b32_e32 v113, 0
	v_mov_b32_e32 v114, 0
	v_mov_b32_e32 v115, 0
	v_mov_b32_e32 v116, 0
	v_mov_b32_e32 v117, 0
	v_mov_b32_e32 v118, 0
	v_mov_b32_e32 v119, 0
	v_mov_b32_e32 v120, 0
	v_mov_b32_e32 v121, 0
	v_mov_b32_e32 v122, 0
	v_mov_b32_e32 v123, 0
	v_mov_b32_e32 v124, 0
	v_mov_b32_e32 v125, 0
	v_mov_b32_e32 v126, 0
	v_mov_b32_e32 v127, 0
	v_mov_b32_e32 v128, 0
	v_mov_b32_e32 v129, 0
	s_cbranch_scc1 .LBB0_649
	s_barrier
; #define WAIT_V(n) asm volatile("s_waitcnt vmcnt(" #n ")" ::: "memory")
; #define BAR __builtin_amdgcn_s_barrier()
; template <bool PRE, bool NEXT> ...
;     ...
;   const int wid = __builtin_amdgcn_readfirstlane(tid >> 6), lane = tid & 63, wr = wid >> 2, wc = wid & 3, fr = lane & 15, fq = lane >> 4;
;   unsigned off0_A, off1_A, off0_Bt, off1_Bt;
;   { int r0, c0, r1, c1; stage_rc(tid * 16, r0, c0); stage_rc(tid * 16 + 8192, r1, c1);
;     off0_A = r0 * lda + c0; off1_A = r1 * lda + c1; off0_Bt = r0 * ldb + c0; off1_Bt = r1 * ldb + c1; }
;   bf16x8 At[4][2], B0[2][2], B1[2][2];
;   const int nt = K / BK;
;   if constexpr (!PRE) {
;     STAGE(SB(0, 0), Bt, ldb, 0, 0); STAGE(SA(0, 0), A, lda, 0, 0);
;     STAGE(SB(0, 1), Bt, ldb, HALF, 0); STAGE(SA(0, 1), A, lda, HALF, 0);
;   }
;   if (wr == 1) BAR;
;   if constexpr (PRE) WAIT_V(0); else WAIT_V(4);
;   BAR;
;   STAGE(SB(1, 0), Bt, ldb, 0, 1); STAGE(SA(1, 0), A, lda, 0, 1); STAGE(SB(1, 1), Bt, ldb, HALF, 1);
;   WAIT_V(6); BAR;
; template <int MODE, bool PRE = false, bool NEXT = false> ...
;     ...
; #pragma unroll
;   for (int ai = 0; ai < 2; ++ai)
; #pragma unroll
;     for (int bj = 0; bj < 2; ++bj)
; #pragma unroll
;       for (int m = 0; m < 4; ++m)
; #pragma unroll
;         for (int n = 0; n < 2; ++n) acc[ai][bj][m][n] = f32x4{0.f, 0.f, 0.f, 0.f};
.LBB0_649:
	v_readlane_b32 s15, v252, 10
	s_mov_b64 s[60:61], 0x80
	v_lshl_add_u64 v[2:3], v[2:3], 0, s[60:61]
	v_add_u32_e32 v155, s15, v18
	v_add_u32_e32 v156, 0x2000, v155
	v_readfirstlane_b32 s14, v155
	s_mov_b32 m0, s14
	v_readfirstlane_b32 s14, v156
	v_add_u32_e32 v157, 0x8000, v147
	s_waitcnt vmcnt(4)
	s_barrier
	global_load_lds_dwordx4 v[2:3], off
	v_lshl_add_u64 v[2:3], v[6:7], 0, s[60:61]
	s_mov_b32 m0, s14
	v_readfirstlane_b32 s14, v157
	s_lshl_b64 s[8:9], s[6:7], 18
	global_load_lds_dwordx4 v[2:3], off
	v_lshl_add_u64 v[2:3], v[8:9], 0, s[60:61]
	s_mov_b32 m0, s14
	v_add_u32_e32 v158, 0xa000, v147
	v_readlane_b32 s22, v252, 11
	global_load_lds_dwordx4 v[2:3], off
	v_lshl_add_u64 v[2:3], v[4:5], 0, s[60:61]
	v_readfirstlane_b32 s14, v158
	s_add_u32 s60, s80, 0x40080
	v_add_u32_e32 v159, s22, v18
	s_mov_b32 m0, s14
	s_addc_u32 s61, s81, 0
	v_readfirstlane_b32 s14, v159
	v_add_u32_e32 v160, 0x2000, v159
	global_load_lds_dwordx4 v[2:3], off
	v_lshl_add_u64 v[2:3], v[0:1], 1, s[60:61]
	s_mov_b32 m0, s14
	v_readfirstlane_b32 s14, v160
	global_load_lds_dwordx4 v[2:3], off
	v_lshl_add_u64 v[2:3], v[130:131], 1, s[60:61]
	s_mov_b32 m0, s14
	v_and_b32_e32 v142, 15, v134
	global_load_lds_dwordx4 v[2:3], off
	v_lshlrev_b32_e32 v3, 2, v134
	s_waitcnt lgkmcnt(0)
	v_and_b32_e32 v19, 48, v134
	v_lshlrev_b32_e32 v2, 6, v142
	v_and_b32_e32 v3, 32, v3
	v_bitop3_b32 v2, v2, v3, v19 bitop3:0x36
	v_add_u32_e32 v6, s33, v2
	v_add_u32_e32 v7, s38, v2
	v_add_u32_e32 v8, s15, v2
	v_add_u32_e32 v9, s22, v2
	v_add_u32_e32 v18, 16, v2
	v_lshlrev_b32_e32 v2, 6, v134
	s_movk_i32 s22, 0x3c0
	v_and_or_b32 v2, v2, s22, v19
	v_xad_u32 v162, v2, v3, 16
	v_lshlrev_b32_e32 v2, 13, v10
	v_and_b32_e32 v2, 0xffffc000, v2
	v_lshlrev_b32_e32 v4, 13, v13
	s_lshl_b32 s14, s58, 6
	s_lshl_b32 s15, s59, 13
	v_lshl_add_u32 v2, v11, 10, v2
	v_and_b32_e32 v4, 0xffffc000, v4
	s_and_b32 s14, s14, 0x3000
	s_or_b32 s59, s15, 0x800
	s_or_b32 s80, s15, 0x1000
	s_or_b32 s81, s15, 0x1800
	v_or_b32_e32 v2, v2, v12
	v_lshl_add_u32 v4, v15, 10, v4
	s_add_u32 s60, s17, s64
	v_add_u32_sdwa v2, v2, sext(v14) dst_sel:DWORD dst_unused:UNUSED_PAD src0_sel:DWORD src1_sel:WORD_0
	v_mov_b32_e32 v3, v1
	v_or_b32_e32 v4, v4, v16
	s_waitcnt vmcnt(6)
	s_addc_u32 s61, 0, s65
	v_lshlrev_b64 v[2:3], 1, v[2:3]
	v_add_u32_sdwa v4, v4, sext(v17) dst_sel:DWORD dst_unused:UNUSED_PAD src0_sel:DWORD src1_sel:WORD_0
	v_mov_b32_e32 v5, v1
	v_lshl_add_u64 v[132:133], s[60:61], 0, v[2:3]
	v_lshlrev_b64 v[4:5], 1, v[4:5]
	v_lshl_add_u64 v[138:139], s[12:13], 0, v[2:3]
	v_mov_b32_e32 v2, 0
	v_lshl_add_u64 v[136:137], s[60:61], 0, v[4:5]
	v_lshl_add_u64 v[140:141], s[12:13], 0, v[4:5]
	s_mov_b32 s12, -2
	v_add_u32_e32 v163, s14, v6
	v_add_u32_e32 v143, s15, v18
	v_add_u32_e32 v161, s14, v7
	v_add_u32_e32 v151, s14, v8
	v_add_u32_e32 v144, s14, v9
	v_mov_b32_e32 v3, v2
	v_mov_b32_e32 v4, v2
	v_mov_b32_e32 v5, v2
	v_mov_b32_e32 v6, v2
	v_mov_b32_e32 v7, v2
	v_mov_b32_e32 v8, v2
	v_mov_b32_e32 v9, v2
	v_mov_b32_e32 v10, v2
	v_mov_b32_e32 v11, v2
	v_mov_b32_e32 v12, v2
	v_mov_b32_e32 v13, v2
	v_mov_b32_e32 v14, v2
	v_mov_b32_e32 v15, v2
	v_mov_b32_e32 v16, v2
	v_mov_b32_e32 v17, v2
	v_mov_b32_e32 v18, v2
	v_mov_b32_e32 v19, v2
	v_mov_b32_e32 v20, v2
	v_mov_b32_e32 v21, v2
	v_mov_b32_e32 v22, v2
	v_mov_b32_e32 v23, v2
	v_mov_b32_e32 v24, v2
	v_mov_b32_e32 v25, v2
	s_waitcnt vmcnt(0)
	s_barrier

; #define BAR __builtin_amdgcn_s_barrier()
; template <bool PRE, bool NEXT> ...
;     ...
;   const int wid = __builtin_amdgcn_readfirstlane(tid >> 6), lane = tid & 63, wr = wid >> 2, wc = wid & 3, fr = lane & 15, fq = lane >> 4;
;   unsigned off0_A, off1_A, off0_Bt, off1_Bt;
;   { int r0, c0, r1, c1; stage_rc(tid * 16, r0, c0); stage_rc(tid * 16 + 8192, r1, c1);
;     off0_A = r0 * lda + c0; off1_A = r1 * lda + c1; off0_Bt = r0 * ldb + c0; off1_Bt = r1 * ldb + c1; }
;   bf16x8 At[4][2], B0[2][2], B1[2][2];
;   const int nt = K / BK;
;   if constexpr (!PRE) {
;     STAGE(SB(0, 0), Bt, ldb, 0, 0); STAGE(SA(0, 0), A, lda, 0, 0);
;     STAGE(SB(0, 1), Bt, ldb, HALF, 0); STAGE(SA(0, 1), A, lda, HALF, 0);
;   }
;   if (wr == 1) BAR;
; template <int MODE, bool PRE = false, bool NEXT = false> ...
;     ...
; #pragma unroll
;   for (int ai = 0; ai < 2; ++ai)
; #pragma unroll
;     for (int bj = 0; bj < 2; ++bj)
; #pragma unroll
;       for (int m = 0; m < 4; ++m)
; #pragma unroll
;         for (int n = 0; n < 2; ++n) acc[ai][bj][m][n] = f32x4{0.f, 0.f, 0.f, 0.f};
.LBB0_909:
	v_mov_b32_e32 v141, v181
	s_barrier
	s_ashr_i32 s9, s8, 31
	v_ashrrev_i32_e32 v0, 31, v141
	v_lshrrev_b32_e32 v0, 26, v0
	v_add_u32_e32 v0, v141, v0
	v_ashrrev_i32_e32 v10, 6, v0
	v_bfe_i32 v0, v141, 27, 1
	v_lshlrev_b32_e32 v18, 4, v141
	v_lshrrev_b32_e32 v0, 22, v0
	v_add_u32_e32 v0, v18, v0
	v_and_b32_e32 v0, 0xfffffc00, v0
	v_sub_u32_e32 v0, v18, v0
	v_lshrrev_b32_e32 v2, 4, v0
	v_bitop3_b32 v2, v2, v0, 32 bitop3:0x6c
	v_ashrrev_i32_e32 v0, 31, v0
	v_lshrrev_b32_e32 v0, 26, v0
	v_lshlrev_b32_e32 v3, 3, v10
	v_add_u32_e32 v0, v2, v0
	v_and_b32_e32 v3, 0x3ffff0, v3
	v_ashrrev_i32_e32 v11, 6, v0
	v_add_u32_e32 v0, v11, v3
	v_lshlrev_b32_e32 v3, 5, v10
	v_and_b32_e32 v12, 32, v3
	v_mul_i32_i24_e32 v3, 64, v11
	v_sub_u32_e32 v2, v2, v3
	v_ashrrev_i16_sdwa v14, v190, sext(v2) dst_sel:DWORD dst_unused:UNUSED_PAD src0_sel:DWORD src1_sel:BYTE_0
	v_add_u32_e32 v2, 0x2000, v18
	v_ashrrev_i32_e32 v3, 31, v2
	v_lshrrev_b32_e32 v3, 22, v3
	v_add_u32_e32 v3, v2, v3
	v_ashrrev_i32_e32 v13, 10, v3
	v_mul_i32_i24_e32 v3, 0x400, v13
	v_sub_u32_e32 v2, v2, v3
	v_lshrrev_b32_e32 v3, 4, v2
	v_bitop3_b32 v2, v3, v2, 32 bitop3:0x6c
	v_ashrrev_i32_e32 v4, 31, v2
	s_lshl_b64 s[10:11], s[8:9], 19
	v_readlane_b32 s0, v253, 58
	v_lshrrev_b32_e32 v4, 26, v4
	s_add_u32 s0, s0, s10
	v_readlane_b32 s1, v253, 59
	v_lshlrev_b32_e32 v3, 3, v13
	v_add_u32_e32 v4, v2, v4
	s_addc_u32 s1, s1, s11
	s_ashr_i32 s7, s6, 31
	v_and_b32_e32 v3, 0x3ffff0, v3
	v_ashrrev_i32_e32 v15, 6, v4
	v_lshlrev_b32_e32 v5, 5, v13
	v_and_b32_e32 v4, 0xc0, v4
	s_lshl_b64 s[12:13], s[6:7], 19
	v_add_u32_e32 v3, v15, v3
	v_and_b32_e32 v16, 32, v5
	v_sub_u32_e32 v2, v2, v4
	v_lshl_or_b32 v0, v0, 10, v12
	s_add_u32 s64, s30, s12
	v_ashrrev_i16_sdwa v17, v190, sext(v2) dst_sel:DWORD dst_unused:UNUSED_PAD src0_sel:DWORD src1_sel:BYTE_0
	v_add_u32_sdwa v0, v0, sext(v14) dst_sel:DWORD dst_unused:UNUSED_PAD src0_sel:DWORD src1_sel:WORD_0
	v_lshl_or_b32 v2, v3, 10, v16
	v_add_u32_e32 v145, s33, v18
	s_addc_u32 s65, s31, s13
	v_add_u32_sdwa v130, v2, sext(v17) dst_sel:DWORD dst_unused:UNUSED_PAD src0_sel:DWORD src1_sel:WORD_0
	v_lshlrev_b64 v[20:21], 1, v[0:1]
	v_readfirstlane_b32 s14, v145
	v_mov_b32_e32 v131, v1
	v_add_u32_e32 v146, 0x2000, v145
	v_readfirstlane_b32 s7, v141
	v_lshl_add_u64 v[2:3], s[64:65], 0, v[20:21]
	s_mov_b32 m0, s14
	v_lshlrev_b64 v[22:23], 1, v[130:131]
	v_readfirstlane_b32 s14, v146
	v_add_u32_e32 v147, 16, v18
	s_ashr_i32 s58, s7, 8
	global_load_lds_dwordx4 v[2:3], off
	v_lshl_add_u64 v[6:7], s[64:65], 0, v[22:23]
	s_mov_b32 m0, s14
	v_readfirstlane_b32 s14, v147
	v_add_u32_e32 v148, 0x2000, v147
	global_load_lds_dwordx4 v[6:7], off
	v_lshl_add_u64 v[8:9], s[0:1], 0, v[20:21]
	s_mov_b32 m0, s14
	v_readfirstlane_b32 s14, v148
	s_add_u32 s60, s64, 0x40000
	v_add_u32_e32 v149, s38, v18
	global_load_lds_dwordx4 v[8:9], off
	v_lshl_add_u64 v[4:5], s[0:1], 0, v[22:23]
	s_mov_b32 m0, s14
	s_addc_u32 s61, s65, 0
	v_readfirstlane_b32 s14, v149
	global_load_lds_dwordx4 v[4:5], off
	v_lshl_add_u64 v[24:25], s[60:61], 0, v[20:21]
	s_mov_b32 m0, s14
	v_add_u32_e32 v151, 0x2000, v149
	global_load_lds_dwordx4 v[24:25], off
	v_lshl_add_u64 v[24:25], s[60:61], 0, v[22:23]
	v_readfirstlane_b32 s14, v151
	s_add_u32 s60, s0, 0x40000
	v_add_u32_e32 v152, 0x4000, v147
	s_mov_b32 m0, s14
	s_addc_u32 s61, s1, 0
	v_readfirstlane_b32 s14, v152
	v_add_u32_e32 v153, 0x6000, v147
	global_load_lds_dwordx4 v[24:25], off
	v_lshl_add_u64 v[20:21], s[60:61], 0, v[20:21]
	s_mov_b32 m0, s14
	v_readfirstlane_b32 s14, v153
	global_load_lds_dwordx4 v[20:21], off
	v_lshl_add_u64 v[20:21], s[60:61], 0, v[22:23]
	s_mov_b32 m0, s14
	s_cmp_lg_u32 s58, 1
	global_load_lds_dwordx4 v[20:21], off
	v_mov_b32_e32 v26, 0
	v_mov_b32_e32 v27, 0
	v_mov_b32_e32 v28, 0
	v_mov_b32_e32 v29, 0
	v_mov_b32_e32 v30, 0
	v_mov_b32_e32 v31, 0
	v_mov_b32_e32 v32, 0
	v_mov_b32_e32 v33, 0
	v_mov_b32_e32 v34, 0
	v_mov_b32_e32 v35, 0
	v_mov_b32_e32 v36, 0
	v_mov_b32_e32 v37, 0
	v_mov_b32_e32 v38, 0
	v_mov_b32_e32 v39, 0
	v_mov_b32_e32 v40, 0
	v_mov_b32_e32 v41, 0
	v_mov_b32_e32 v42, 0
	v_mov_b32_e32 v43, 0
	v_mov_b32_e32 v44, 0
	v_mov_b32_e32 v45, 0
	v_mov_b32_e32 v46, 0
	v_mov_b32_e32 v47, 0
	v_mov_b32_e32 v48, 0
	v_mov_b32_e32 v49, 0
	v_mov_b32_e32 v50, 0
	v_mov_b32_e32 v51, 0
	v_mov_b32_e32 v52, 0
	v_mov_b32_e32 v53, 0
	v_mov_b32_e32 v54, 0
	v_mov_b32_e32 v55, 0
	v_mov_b32_e32 v56, 0
	v_mov_b32_e32 v57, 0
	v_mov_b32_e32 v58, 0
	v_mov_b32_e32 v59, 0
	v_mov_b32_e32 v60, 0
	v_mov_b32_e32 v61, 0
	v_mov_b32_e32 v62, 0
	v_mov_b32_e32 v63, 0
	v_mov_b32_e32 v64, 0
	v_mov_b32_e32 v65, 0
	v_mov_b32_e32 v66, 0
	v_mov_b32_e32 v67, 0
	v_mov_b32_e32 v68, 0
	v_mov_b32_e32 v69, 0
	v_mov_b32_e32 v70, 0
	v_mov_b32_e32 v71, 0
	v_mov_b32_e32 v72, 0
	v_mov_b32_e32 v73, 0
	v_mov_b32_e32 v74, 0
	v_mov_b32_e32 v75, 0
	v_mov_b32_e32 v76, 0
	v_mov_b32_e32 v77, 0
	v_mov_b32_e32 v78, 0
	v_mov_b32_e32 v79, 0
	v_mov_b32_e32 v80, 0
	v_mov_b32_e32 v81, 0
	v_mov_b32_e32 v82, 0
	v_mov_b32_e32 v83, 0
	v_mov_b32_e32 v84, 0
	v_mov_b32_e32 v85, 0
	v_mov_b32_e32 v86, 0
	v_mov_b32_e32 v87, 0
	v_mov_b32_e32 v88, 0
	v_mov_b32_e32 v89, 0
	v_mov_b32_e32 v90, 0
	v_mov_b32_e32 v91, 0
	v_mov_b32_e32 v92, 0
	v_mov_b32_e32 v93, 0
	v_mov_b32_e32 v94, 0
	v_mov_b32_e32 v95, 0
	v_mov_b32_e32 v96, 0
	v_mov_b32_e32 v97, 0
	v_mov_b32_e32 v98, 0
	v_mov_b32_e32 v99, 0
	v_mov_b32_e32 v100, 0
	v_mov_b32_e32 v101, 0
	v_mov_b32_e32 v102, 0
	v_mov_b32_e32 v103, 0
	v_mov_b32_e32 v104, 0
	v_mov_b32_e32 v105, 0
	v_mov_b32_e32 v106, 0
	v_mov_b32_e32 v107, 0
	v_mov_b32_e32 v108, 0
	v_mov_b32_e32 v109, 0
	v_mov_b32_e32 v110, 0
	v_mov_b32_e32 v111, 0
	v_mov_b32_e32 v112, 0
	v_mov_b32_e32 v113, 0
	v_mov_b32_e32 v114, 0
	v_mov_b32_e32 v115, 0
	v_mov_b32_e32 v116, 0
	v_mov_b32_e32 v117, 0
	v_mov_b32_e32 v118, 0
	v_mov_b32_e32 v119, 0
	v_mov_b32_e32 v120, 0
	v_mov_b32_e32 v121, 0
	v_mov_b32_e32 v122, 0
	v_mov_b32_e32 v123, 0
	v_mov_b32_e32 v124, 0
	v_mov_b32_e32 v125, 0
	v_mov_b32_e32 v126, 0
	v_mov_b32_e32 v127, 0
	v_mov_b32_e32 v128, 0
	v_mov_b32_e32 v129, 0
	s_cbranch_scc1 .LBB0_911
	s_barrier
; #define WAIT_V(n) asm volatile("s_waitcnt vmcnt(" #n ")" ::: "memory")
; #define BAR __builtin_amdgcn_s_barrier()
; template <bool PRE, bool NEXT> ...
;     ...
;   const int wid = __builtin_amdgcn_readfirstlane(tid >> 6), lane = tid & 63, wr = wid >> 2, wc = wid & 3, fr = lane & 15, fq = lane >> 4;
;   unsigned off0_A, off1_A, off0_Bt, off1_Bt;
;   { int r0, c0, r1, c1; stage_rc(tid * 16, r0, c0); stage_rc(tid * 16 + 8192, r1, c1);
;     off0_A = r0 * lda + c0; off1_A = r1 * lda + c1; off0_Bt = r0 * ldb + c0; off1_Bt = r1 * ldb + c1; }
;   bf16x8 At[4][2], B0[2][2], B1[2][2];
;   const int nt = K / BK;
;   if constexpr (!PRE) {
;     STAGE(SB(0, 0), Bt, ldb, 0, 0); STAGE(SA(0, 0), A, lda, 0, 0);
;     STAGE(SB(0, 1), Bt, ldb, HALF, 0); STAGE(SA(0, 1), A, lda, HALF, 0);
;   }
;   if (wr == 1) BAR;
;   if constexpr (PRE) WAIT_V(0); else WAIT_V(4);
;   BAR;
;   STAGE(SB(1, 0), Bt, ldb, 0, 1); STAGE(SA(1, 0), A, lda, 0, 1); STAGE(SB(1, 1), Bt, ldb, HALF, 1);
;   WAIT_V(6); BAR;
; template <int MODE, bool PRE = false, bool NEXT = false> ...
;     ...
; #pragma unroll
;   for (int ai = 0; ai < 2; ++ai)
; #pragma unroll
;     for (int bj = 0; bj < 2; ++bj)
; #pragma unroll
;       for (int m = 0; m < 4; ++m)
; #pragma unroll
;         for (int n = 0; n < 2; ++n) acc[ai][bj][m][n] = f32x4{0.f, 0.f, 0.f, 0.f};
.LBB0_911:
	v_readlane_b32 s15, v252, 10
	s_mov_b64 s[60:61], 0x80
	v_lshl_add_u64 v[2:3], v[2:3], 0, s[60:61]
	v_add_u32_e32 v154, s15, v18
	v_add_u32_e32 v155, 0x2000, v154
	v_readfirstlane_b32 s14, v154
	s_mov_b32 m0, s14
	v_readfirstlane_b32 s14, v155
	v_add_u32_e32 v156, 0x8000, v147
	s_waitcnt vmcnt(4)
	s_barrier
	global_load_lds_dwordx4 v[2:3], off
	v_lshl_add_u64 v[2:3], v[6:7], 0, s[60:61]
	s_mov_b32 m0, s14
	v_readfirstlane_b32 s14, v156
	global_load_lds_dwordx4 v[2:3], off
	v_lshl_add_u64 v[2:3], v[8:9], 0, s[60:61]
	s_mov_b32 m0, s14
	v_add_u32_e32 v157, 0xa000, v147
	v_readlane_b32 s22, v252, 11
	global_load_lds_dwordx4 v[2:3], off
	v_lshl_add_u64 v[2:3], v[4:5], 0, s[60:61]
	v_readfirstlane_b32 s14, v157
	s_add_u32 s60, s64, 0x40080
	v_add_u32_e32 v158, s22, v18
	s_mov_b32 m0, s14
	s_addc_u32 s61, s65, 0
	v_readfirstlane_b32 s14, v158
	v_add_u32_e32 v159, 0x2000, v158
	global_load_lds_dwordx4 v[2:3], off
	v_lshl_add_u64 v[2:3], v[0:1], 1, s[60:61]
	s_mov_b32 m0, s14
	v_readfirstlane_b32 s14, v159
	global_load_lds_dwordx4 v[2:3], off
	v_lshl_add_u64 v[2:3], v[130:131], 1, s[60:61]
	s_mov_b32 m0, s14
	v_and_b32_e32 v142, 15, v141
	global_load_lds_dwordx4 v[2:3], off
	v_lshlrev_b32_e32 v3, 2, v141
	v_and_b32_e32 v19, 48, v141
	v_lshlrev_b32_e32 v2, 6, v142
	v_and_b32_e32 v3, 32, v3
	v_bitop3_b32 v2, v2, v3, v19 bitop3:0x36
	v_add_u32_e32 v6, s33, v2
	v_add_u32_e32 v7, s38, v2
	v_add_u32_e32 v8, s15, v2
	v_add_u32_e32 v9, s22, v2
	v_add_u32_e32 v18, 16, v2
	v_lshlrev_b32_e32 v2, 6, v141
	s_movk_i32 s22, 0x3c0
	v_and_or_b32 v2, v2, s22, v19
	v_xad_u32 v161, v2, v3, 16
	v_lshlrev_b32_e32 v2, 13, v10
	v_and_b32_e32 v2, 0xffffc000, v2
	v_lshlrev_b32_e32 v4, 13, v13
	s_lshl_b32 s14, s7, 6
	s_lshl_b32 s15, s58, 13
	v_lshl_add_u32 v2, v11, 10, v2
	v_and_b32_e32 v4, 0xffffc000, v4
	s_and_b32 s14, s14, 0x3000
	s_or_b32 s58, s15, 0x800
	s_or_b32 s59, s15, 0x1000
	s_or_b32 s64, s15, 0x1800
	v_or_b32_e32 v2, v2, v12
	v_lshl_add_u32 v4, v15, 10, v4
	s_add_u32 s12, s17, s12
	v_add_u32_sdwa v2, v2, sext(v14) dst_sel:DWORD dst_unused:UNUSED_PAD src0_sel:DWORD src1_sel:WORD_0
	v_mov_b32_e32 v3, v1
	v_or_b32_e32 v4, v4, v16
	s_waitcnt vmcnt(6)
	s_addc_u32 s13, 0, s13
	v_lshlrev_b64 v[2:3], 1, v[2:3]
	v_add_u32_sdwa v4, v4, sext(v17) dst_sel:DWORD dst_unused:UNUSED_PAD src0_sel:DWORD src1_sel:WORD_0
	v_mov_b32_e32 v5, v1
	v_lshl_add_u64 v[132:133], s[12:13], 0, v[2:3]
	v_lshlrev_b64 v[4:5], 1, v[4:5]
	v_lshl_add_u64 v[136:137], s[10:11], 0, v[2:3]
	v_mov_b32_e32 v2, 0
	v_lshl_add_u64 v[134:135], s[12:13], 0, v[4:5]
	v_lshl_add_u64 v[138:139], s[10:11], 0, v[4:5]
	s_mov_b32 s10, -2
	v_add_u32_e32 v162, s14, v6
	v_add_u32_e32 v143, s15, v18
	v_add_u32_e32 v160, s14, v7
	v_add_u32_e32 v150, s14, v8
	v_add_u32_e32 v144, s14, v9
	v_mov_b32_e32 v3, v2
	v_mov_b32_e32 v4, v2
	v_mov_b32_e32 v5, v2
	v_mov_b32_e32 v6, v2
	v_mov_b32_e32 v7, v2
	v_mov_b32_e32 v8, v2
	v_mov_b32_e32 v9, v2
	v_mov_b32_e32 v10, v2
	v_mov_b32_e32 v11, v2
	v_mov_b32_e32 v12, v2
	v_mov_b32_e32 v13, v2
	v_mov_b32_e32 v14, v2
	v_mov_b32_e32 v15, v2
	v_mov_b32_e32 v16, v2
	v_mov_b32_e32 v17, v2
	v_mov_b32_e32 v18, v2
	v_mov_b32_e32 v19, v2
	v_mov_b32_e32 v20, v2
	v_mov_b32_e32 v21, v2
	v_mov_b32_e32 v22, v2
	v_mov_b32_e32 v23, v2
	v_mov_b32_e32 v24, v2
	v_mov_b32_e32 v25, v2
	s_barrier

; #define BAR __builtin_amdgcn_s_barrier()
; template <bool PRE, bool NEXT> ...
;     ...
;   const int wid = __builtin_amdgcn_readfirstlane(tid >> 6), lane = tid & 63, wr = wid >> 2, wc = wid & 3, fr = lane & 15, fq = lane >> 4;
;   unsigned off0_A, off1_A, off0_Bt, off1_Bt;
;   { int r0, c0, r1, c1; stage_rc(tid * 16, r0, c0); stage_rc(tid * 16 + 8192, r1, c1);
;     off0_A = r0 * lda + c0; off1_A = r1 * lda + c1; off0_Bt = r0 * ldb + c0; off1_Bt = r1 * ldb + c1; }
;   bf16x8 At[4][2], B0[2][2], B1[2][2];
;   const int nt = K / BK;
;   if constexpr (!PRE) {
;     STAGE(SB(0, 0), Bt, ldb, 0, 0); STAGE(SA(0, 0), A, lda, 0, 0);
;     STAGE(SB(0, 1), Bt, ldb, HALF, 0); STAGE(SA(0, 1), A, lda, HALF, 0);
;   }
;   if (wr == 1) BAR;
; template <int MODE, bool PRE = false, bool NEXT = false> ...
;     ...
; #pragma unroll
;   for (int ai = 0; ai < 2; ++ai)
; #pragma unroll
;     for (int bj = 0; bj < 2; ++bj)
; #pragma unroll
;       for (int m = 0; m < 4; ++m)
; #pragma unroll
;         for (int n = 0; n < 2; ++n) acc[ai][bj][m][n] = f32x4{0.f, 0.f, 0.f, 0.f};
.LBB0_963:
	v_mov_b32_e32 v130, v181
	s_barrier
	s_ashr_i32 s7, s6, 31
	v_ashrrev_i32_e32 v131, 31, v130
	v_lshrrev_b32_e32 v0, 26, v131
	v_add_u32_e32 v0, v130, v0
	v_ashrrev_i32_e32 v10, 6, v0
	v_bfe_i32 v0, v130, 27, 1
	v_lshlrev_b32_e32 v18, 4, v130
	v_lshrrev_b32_e32 v0, 22, v0
	v_add_u32_e32 v0, v18, v0
	v_and_b32_e32 v0, 0xfffffc00, v0
	v_sub_u32_e32 v0, v18, v0
	v_lshrrev_b32_e32 v2, 4, v0
	v_bitop3_b32 v2, v2, v0, 32 bitop3:0x6c
	v_ashrrev_i32_e32 v0, 31, v0
	v_lshrrev_b32_e32 v0, 26, v0
	v_lshlrev_b32_e32 v3, 3, v10
	v_add_u32_e32 v0, v2, v0
	v_and_b32_e32 v3, 0xfffff0, v3
	v_ashrrev_i32_e32 v12, 6, v0
	v_add_u32_e32 v0, v12, v3
	v_lshlrev_b32_e32 v3, 5, v10
	v_and_b32_e32 v11, 32, v3
	v_mul_i32_i24_e32 v3, 64, v12
	v_sub_u32_e32 v2, v2, v3
	v_ashrrev_i16_sdwa v14, v190, sext(v2) dst_sel:DWORD dst_unused:UNUSED_PAD src0_sel:DWORD src1_sel:BYTE_0
	v_add_u32_e32 v2, 0x2000, v18
	v_ashrrev_i32_e32 v3, 31, v2
	v_lshrrev_b32_e32 v3, 22, v3
	v_add_u32_e32 v3, v2, v3
	v_ashrrev_i32_e32 v13, 10, v3
	v_mul_i32_i24_e32 v3, 0x400, v13
	v_sub_u32_e32 v2, v2, v3
	v_lshrrev_b32_e32 v3, 4, v2
	v_bitop3_b32 v2, v3, v2, 32 bitop3:0x6c
	v_ashrrev_i32_e32 v4, 31, v2
	v_lshrrev_b32_e32 v4, 26, v4
	v_lshlrev_b32_e32 v3, 3, v13
	v_add_u32_e32 v4, v2, v4
	s_mul_i32 s10, s6, 0x160000
	v_readlane_b32 s1, v253, 60
	v_and_b32_e32 v3, 0xfffff0, v3
	v_ashrrev_i32_e32 v16, 6, v4
	v_and_b32_e32 v4, 0xc0, v4
	s_movk_i32 s14, 0xb00
	s_mul_hi_i32 s11, s6, 0x160000
	s_add_u32 s8, s1, s10
	v_readlane_b32 s1, v253, 61
	v_add_u32_e32 v3, v16, v3
	v_lshlrev_b32_e32 v5, 5, v13
	v_sub_u32_e32 v2, v2, v4
	v_mul_lo_u32 v0, v0, s14
	s_addc_u32 s9, s1, s11
	s_ashr_i32 s1, s0, 31
	s_mul_i32 s80, s0, 0x160000
	v_and_b32_e32 v15, 32, v5
	v_ashrrev_i16_sdwa v17, v190, sext(v2) dst_sel:DWORD dst_unused:UNUSED_PAD src0_sel:DWORD src1_sel:BYTE_0
	v_or_b32_e32 v0, v0, v11
	v_mul_lo_u32 v2, v3, s14
	s_mul_hi_i32 s65, s0, 0x160000
	s_add_u32 s12, s30, s80
	v_add_u32_sdwa v0, v0, sext(v14) dst_sel:DWORD dst_unused:UNUSED_PAD src0_sel:DWORD src1_sel:WORD_0
	v_or_b32_e32 v2, v2, v15
	v_add_u32_e32 v145, s33, v18
	s_addc_u32 s13, s31, s65
	v_add_u32_sdwa v132, v2, sext(v17) dst_sel:DWORD dst_unused:UNUSED_PAD src0_sel:DWORD src1_sel:WORD_0
	v_lshlrev_b64 v[20:21], 1, v[0:1]
	v_readfirstlane_b32 s14, v145
	v_mov_b32_e32 v133, v1
	v_add_u32_e32 v147, 0x2000, v145
	v_readfirstlane_b32 s59, v130
	v_lshl_add_u64 v[2:3], s[12:13], 0, v[20:21]
	s_mov_b32 m0, s14
	v_lshlrev_b64 v[22:23], 1, v[132:133]
	v_readfirstlane_b32 s14, v147
	v_add_u32_e32 v148, 16, v18
	s_ashr_i32 s64, s59, 8
	global_load_lds_dwordx4 v[2:3], off
	v_lshl_add_u64 v[6:7], s[12:13], 0, v[22:23]
	s_mov_b32 m0, s14
	v_readfirstlane_b32 s14, v148
	v_add_u32_e32 v149, 0x2000, v148
	global_load_lds_dwordx4 v[6:7], off
	v_lshl_add_u64 v[8:9], s[8:9], 0, v[20:21]
	s_mov_b32 m0, s14
	v_readfirstlane_b32 s14, v149
	s_add_u32 s60, s12, 0xb0000
	v_add_u32_e32 v150, s38, v18
	global_load_lds_dwordx4 v[8:9], off
	v_lshl_add_u64 v[4:5], s[8:9], 0, v[22:23]
	s_mov_b32 m0, s14
	s_addc_u32 s61, s13, 0
	v_readfirstlane_b32 s14, v150
	global_load_lds_dwordx4 v[4:5], off
	v_lshl_add_u64 v[24:25], s[60:61], 0, v[20:21]
	s_mov_b32 m0, s14
	v_add_u32_e32 v151, 0x2000, v150
	global_load_lds_dwordx4 v[24:25], off
	v_lshl_add_u64 v[24:25], s[60:61], 0, v[22:23]
	v_readfirstlane_b32 s14, v151
	s_add_u32 s60, s8, 0xb0000
	v_add_u32_e32 v153, 0x4000, v148
	s_mov_b32 m0, s14
	s_addc_u32 s61, s9, 0
	v_readfirstlane_b32 s14, v153
	v_add_u32_e32 v154, 0x6000, v148
	global_load_lds_dwordx4 v[24:25], off
	v_lshl_add_u64 v[20:21], s[60:61], 0, v[20:21]
	s_mov_b32 m0, s14
	v_readfirstlane_b32 s14, v154
	global_load_lds_dwordx4 v[20:21], off
	v_lshl_add_u64 v[20:21], s[60:61], 0, v[22:23]
	s_mov_b32 m0, s14
	s_cmp_lg_u32 s64, 1
	global_load_lds_dwordx4 v[20:21], off
	v_mov_b32_e32 v26, 0
	v_mov_b32_e32 v27, 0
	v_mov_b32_e32 v28, 0
	v_mov_b32_e32 v29, 0
	v_mov_b32_e32 v30, 0
	v_mov_b32_e32 v31, 0
	v_mov_b32_e32 v32, 0
	v_mov_b32_e32 v33, 0
	v_mov_b32_e32 v34, 0
	v_mov_b32_e32 v35, 0
	v_mov_b32_e32 v36, 0
	v_mov_b32_e32 v37, 0
	v_mov_b32_e32 v38, 0
	v_mov_b32_e32 v39, 0
	v_mov_b32_e32 v40, 0
	v_mov_b32_e32 v41, 0
	v_mov_b32_e32 v42, 0
	v_mov_b32_e32 v43, 0
	v_mov_b32_e32 v44, 0
	v_mov_b32_e32 v45, 0
	v_mov_b32_e32 v46, 0
	v_mov_b32_e32 v47, 0
	v_mov_b32_e32 v48, 0
	v_mov_b32_e32 v49, 0
	v_mov_b32_e32 v50, 0
	v_mov_b32_e32 v51, 0
	v_mov_b32_e32 v52, 0
	v_mov_b32_e32 v53, 0
	v_mov_b32_e32 v54, 0
	v_mov_b32_e32 v55, 0
	v_mov_b32_e32 v56, 0
	v_mov_b32_e32 v57, 0
	v_mov_b32_e32 v58, 0
	v_mov_b32_e32 v59, 0
	v_mov_b32_e32 v60, 0
	v_mov_b32_e32 v61, 0
	v_mov_b32_e32 v62, 0
	v_mov_b32_e32 v63, 0
	v_mov_b32_e32 v64, 0
	v_mov_b32_e32 v65, 0
	v_mov_b32_e32 v66, 0
	v_mov_b32_e32 v67, 0
	v_mov_b32_e32 v68, 0
	v_mov_b32_e32 v69, 0
	v_mov_b32_e32 v70, 0
	v_mov_b32_e32 v71, 0
	v_mov_b32_e32 v72, 0
	v_mov_b32_e32 v73, 0
	v_mov_b32_e32 v74, 0
	v_mov_b32_e32 v75, 0
	v_mov_b32_e32 v76, 0
	v_mov_b32_e32 v77, 0
	v_mov_b32_e32 v78, 0
	v_mov_b32_e32 v79, 0
	v_mov_b32_e32 v80, 0
	v_mov_b32_e32 v81, 0
	v_mov_b32_e32 v82, 0
	v_mov_b32_e32 v83, 0
	v_mov_b32_e32 v84, 0
	v_mov_b32_e32 v85, 0
	v_mov_b32_e32 v86, 0
	v_mov_b32_e32 v87, 0
	v_mov_b32_e32 v88, 0
	v_mov_b32_e32 v89, 0
	v_mov_b32_e32 v90, 0
	v_mov_b32_e32 v91, 0
	v_mov_b32_e32 v92, 0
	v_mov_b32_e32 v93, 0
	v_mov_b32_e32 v94, 0
	v_mov_b32_e32 v95, 0
	v_mov_b32_e32 v96, 0
	v_mov_b32_e32 v97, 0
	v_mov_b32_e32 v98, 0
	v_mov_b32_e32 v99, 0
	v_mov_b32_e32 v100, 0
	v_mov_b32_e32 v101, 0
	v_mov_b32_e32 v102, 0
	v_mov_b32_e32 v103, 0
	v_mov_b32_e32 v104, 0
	v_mov_b32_e32 v105, 0
	v_mov_b32_e32 v106, 0
	v_mov_b32_e32 v107, 0
	v_mov_b32_e32 v108, 0
	v_mov_b32_e32 v109, 0
	v_mov_b32_e32 v110, 0
	v_mov_b32_e32 v111, 0
	v_mov_b32_e32 v112, 0
	v_mov_b32_e32 v113, 0
	v_mov_b32_e32 v114, 0
	v_mov_b32_e32 v115, 0
	v_mov_b32_e32 v116, 0
	v_mov_b32_e32 v117, 0
	v_mov_b32_e32 v118, 0
	v_mov_b32_e32 v119, 0
	v_mov_b32_e32 v120, 0
	v_mov_b32_e32 v121, 0
	v_mov_b32_e32 v122, 0
	v_mov_b32_e32 v123, 0
	v_mov_b32_e32 v124, 0
	v_mov_b32_e32 v125, 0
	v_mov_b32_e32 v126, 0
	v_mov_b32_e32 v127, 0
	v_mov_b32_e32 v128, 0
	v_mov_b32_e32 v129, 0
	s_cbranch_scc1 .LBB0_965
	s_barrier
; #define WAIT_V(n) asm volatile("s_waitcnt vmcnt(" #n ")" ::: "memory")
; #define BAR __builtin_amdgcn_s_barrier()
; template <bool PRE, bool NEXT> ...
;     ...
;   const int wid = __builtin_amdgcn_readfirstlane(tid >> 6), lane = tid & 63, wr = wid >> 2, wc = wid & 3, fr = lane & 15, fq = lane >> 4;
;   unsigned off0_A, off1_A, off0_Bt, off1_Bt;
;   { int r0, c0, r1, c1; stage_rc(tid * 16, r0, c0); stage_rc(tid * 16 + 8192, r1, c1);
;     off0_A = r0 * lda + c0; off1_A = r1 * lda + c1; off0_Bt = r0 * ldb + c0; off1_Bt = r1 * ldb + c1; }
;   bf16x8 At[4][2], B0[2][2], B1[2][2];
;   const int nt = K / BK;
;   if constexpr (!PRE) {
;     STAGE(SB(0, 0), Bt, ldb, 0, 0); STAGE(SA(0, 0), A, lda, 0, 0);
;     STAGE(SB(0, 1), Bt, ldb, HALF, 0); STAGE(SA(0, 1), A, lda, HALF, 0);
;   }
;   if (wr == 1) BAR;
;   if constexpr (PRE) WAIT_V(0); else WAIT_V(4);
;   BAR;
;   STAGE(SB(1, 0), Bt, ldb, 0, 1); STAGE(SA(1, 0), A, lda, 0, 1); STAGE(SB(1, 1), Bt, ldb, HALF, 1);
;   WAIT_V(6); BAR;
; template <int MODE, bool PRE = false, bool NEXT = false> ...
;     ...
; #pragma unroll
;   for (int ai = 0; ai < 2; ++ai)
; #pragma unroll
;     for (int bj = 0; bj < 2; ++bj)
; #pragma unroll
;       for (int m = 0; m < 4; ++m)
; #pragma unroll
;         for (int n = 0; n < 2; ++n) acc[ai][bj][m][n] = f32x4{0.f, 0.f, 0.f, 0.f};
.LBB0_965:
	v_readlane_b32 s15, v252, 10
	s_mov_b64 s[60:61], 0x80
	v_lshl_add_u64 v[2:3], v[2:3], 0, s[60:61]
	v_add_u32_e32 v155, s15, v18
	v_add_u32_e32 v156, 0x2000, v155
	v_readfirstlane_b32 s14, v155
	s_mov_b32 m0, s14
	v_readfirstlane_b32 s14, v156
	v_add_u32_e32 v157, 0x8000, v148
	s_waitcnt vmcnt(4)
	s_barrier
	global_load_lds_dwordx4 v[2:3], off
	v_lshl_add_u64 v[2:3], v[6:7], 0, s[60:61]
	s_mov_b32 m0, s14
	v_readfirstlane_b32 s14, v157
	v_add_u32_e32 v158, 0xa000, v148
	v_readlane_b32 s22, v252, 11
	global_load_lds_dwordx4 v[2:3], off
	v_lshl_add_u64 v[2:3], v[8:9], 0, s[60:61]
	s_mov_b32 m0, s14
	v_readfirstlane_b32 s14, v158
	s_add_u32 s12, s12, 0xb0080
	v_add_u32_e32 v159, s22, v18
	global_load_lds_dwordx4 v[2:3], off
	v_lshl_add_u64 v[2:3], v[4:5], 0, s[60:61]
	s_mov_b32 m0, s14
	s_addc_u32 s13, s13, 0
	v_readfirstlane_b32 s14, v159
	global_load_lds_dwordx4 v[2:3], off
	v_lshl_add_u64 v[2:3], v[0:1], 1, s[12:13]
	s_mov_b32 m0, s14
	v_add_u32_e32 v160, 0x2000, v159
	global_load_lds_dwordx4 v[2:3], off
	v_lshl_add_u64 v[2:3], v[132:133], 1, s[12:13]
	v_readfirstlane_b32 s12, v160
	s_mov_b32 m0, s12
	v_and_b32_e32 v143, 15, v130
	global_load_lds_dwordx4 v[2:3], off
	v_lshlrev_b32_e32 v3, 2, v130
	v_and_b32_e32 v19, 48, v130
	v_lshlrev_b32_e32 v2, 6, v143
	v_and_b32_e32 v3, 32, v3
	v_bitop3_b32 v2, v2, v3, v19 bitop3:0x36
	s_lshl_b32 s12, s59, 6
	v_add_u32_e32 v6, s33, v2
	v_add_u32_e32 v7, s38, v2
	v_add_u32_e32 v8, s15, v2
	v_add_u32_e32 v9, s22, v2
	s_and_b32 s14, s12, 0x3000
	s_lshl_b32 s15, s64, 13
	v_add_u32_e32 v18, 16, v2
	v_lshlrev_b32_e32 v2, 6, v130
	s_movk_i32 s12, 0x3c0
	v_and_or_b32 v2, v2, s12, v19
	s_or_b32 s12, s15, 0x800
	s_or_b32 s13, s15, 0x1000
	s_or_b32 s64, s15, 0x1800
	s_add_u32 s60, s17, s80
	s_movk_i32 s22, 0xb00
	v_xad_u32 v162, v2, v3, 16
	s_addc_u32 s61, 0, s65
	v_lshrrev_b32_e32 v3, 1, v10
	v_mul_lo_u32 v2, v12, s22
	s_mov_b32 s65, 0xb000
	v_mad_u64_u32 v[2:3], s[80:81], v3, s65, v[2:3]
	v_lshrrev_b32_e32 v5, 1, v13
	v_mul_lo_u32 v4, v16, s22
	v_or_b32_e32 v2, v2, v11
	v_mad_u64_u32 v[4:5], s[80:81], v5, s65, v[4:5]
	v_add_u32_sdwa v2, v2, sext(v14) dst_sel:DWORD dst_unused:UNUSED_PAD src0_sel:DWORD src1_sel:WORD_0
	v_mov_b32_e32 v3, v1
	v_or_b32_e32 v4, v4, v15
	s_waitcnt vmcnt(6)
	v_lshlrev_b64 v[2:3], 1, v[2:3]
	v_add_u32_sdwa v4, v4, sext(v17) dst_sel:DWORD dst_unused:UNUSED_PAD src0_sel:DWORD src1_sel:WORD_0
	v_mov_b32_e32 v5, v1
	v_lshl_add_u64 v[134:135], s[60:61], 0, v[2:3]
	v_lshlrev_b64 v[4:5], 1, v[4:5]
	v_lshl_add_u64 v[138:139], s[10:11], 0, v[2:3]
	v_mov_b32_e32 v2, 0
	v_lshl_add_u64 v[136:137], s[60:61], 0, v[4:5]
	v_lshl_add_u64 v[140:141], s[10:11], 0, v[4:5]
	s_mov_b32 s10, -2
	v_add_u32_e32 v163, s14, v6
	v_add_u32_e32 v144, s15, v18
	v_add_u32_e32 v161, s14, v7
	v_add_u32_e32 v152, s14, v8
	v_add_u32_e32 v146, s14, v9
	v_mov_b32_e32 v3, v2
	v_mov_b32_e32 v4, v2
	v_mov_b32_e32 v5, v2
	v_mov_b32_e32 v6, v2
	v_mov_b32_e32 v7, v2
	v_mov_b32_e32 v8, v2
	v_mov_b32_e32 v9, v2
	v_mov_b32_e32 v10, v2
	v_mov_b32_e32 v11, v2
	v_mov_b32_e32 v12, v2
	v_mov_b32_e32 v13, v2
	v_mov_b32_e32 v14, v2
	v_mov_b32_e32 v15, v2
	v_mov_b32_e32 v16, v2
	v_mov_b32_e32 v17, v2
	v_mov_b32_e32 v18, v2
	v_mov_b32_e32 v19, v2
	v_mov_b32_e32 v20, v2
	v_mov_b32_e32 v21, v2
	v_mov_b32_e32 v22, v2
	v_mov_b32_e32 v23, v2
	v_mov_b32_e32 v24, v2
	v_mov_b32_e32 v25, v2
	s_barrier
